# v26: loop-edge edit - ring rotation and loop counter scalar ops hoisted in front of the last tail MFMA of each tile (both wave groups)
# speedup vs baseline: 1.0073x; 1.0073x over previous
; #define SBAR() __builtin_amdgcn_sched_barrier(0)
; #define PVR(S, DA, DB, vbase) do { S[0] = tr_read<v_rd_off(DA, 0, 0)>(vbase); S[1] = tr_read<v_rd_off(DA, 0, 1)>(vbase); S[2] = tr_read<v_rd_off(DB, 0, 0)>(vbase); S[3] = tr_read<v_rd_off(DB, 0, 1)>(vbase); \
;     S[4] = tr_read<v_rd_off(DA, 1, 0)>(vbase); S[5] = tr_read<v_rd_off(DA, 1, 1)>(vbase); S[6] = tr_read<v_rd_off(DB, 1, 0)>(vbase); S[7] = tr_read<v_rd_off(DB, 1, 1)>(vbase); } while (0)
; #define RAWBAR() do { asm volatile("s_waitcnt lgkmcnt(0)" ::: "memory"); __builtin_amdgcn_s_barrier(); asm volatile("" ::: "memory"); } while (0)
; #define RAWBAR() do { asm volatile("s_waitcnt lgkmcnt(0)" ::: "memory"); __builtin_amdgcn_s_barrier(); asm volatile("" ::: "memory"); } while (0)
; #define RAWBAR() do { asm volatile("s_waitcnt lgkmcnt(0)" ::: "memory"); __builtin_amdgcn_s_barrier(); asm volatile("" ::: "memory"); } while (0)
; #define RAWBAR() do { asm volatile("s_waitcnt lgkmcnt(0)" ::: "memory"); __builtin_amdgcn_s_barrier(); asm volatile("" ::: "memory"); } while (0)
; #define RAWBAR() do { asm volatile("s_waitcnt lgkmcnt(0)" ::: "memory"); __builtin_amdgcn_s_barrier(); asm volatile("" ::: "memory"); } while (0)
; template <int MODE> ...
;     ...
;   for (int j = 0; j < NT; ++j) {
;     const int buf = j & 1;
;     if (j + 1 < NT) { STAGE((j + 1) * KVBLK, buf ^ 1); }
;     const char* Kb = K_lds + buf * 16384;
;     f32x16 pe = {}, po = {};
; #pragma unroll
;     for (int d0 = 0; d0 < 8; d0 += 2) {
;       const bf16x8 k0 = *reinterpret_cast<const bf16x8*>(Kb + KSWZ(krow, (d0 * 16 + hi * 8) * 2));
;       const bf16x8 k1 = *reinterpret_cast<const bf16x8*>(Kb + KSWZ(krow, ((d0 + 1) * 16 + hi * 8) * 2));
;       pe = __builtin_amdgcn_mfma_f32_32x32x16_bf16(k0, qr[d0], pe, 0, 0, 0);
;       po = __builtin_amdgcn_mfma_f32_32x32x16_bf16(k1, qr[d0 + 1], po, 0, 0, 0); }
;     const int vo = vb0 + buf * 32768;
;     s16x4 R0_[8], R1_[8];
;     PVR(R0_, 0, 1, vo);
;     f32x16 p;
; #pragma unroll
;     for (int r = 0; r < 16; ++r) p[r] = __builtin_amdgcn_exp2f(fmaf(pe[r] + po[r], C, negMc));
;     float ps = 0.f;
; #pragma unroll
;     for (int r = 0; r < 16; ++r) ps += p[r];
;     lsum += ps;
;     const bf16x8 own0 = pk8(p, 0), own1 = pk8(p, 8);
;     SBAR();
;     PV_TAIL4(o, vo, vo + 16384, own0, own1);
;     asm volatile("s_waitcnt vmcnt(0)" ::: "memory");
;     RAWBAR();
;   }
.LBB0_1019:
	ds_read_b128 v[226:229], v225 offset:16384
	ds_read_b128 v[230:233], v223 offset:16384
	ds_read_b128 v[234:237], v222 offset:16384
	ds_read_b128 v[238:241], v221 offset:16384
	v_exp_f32_e32 v144, v144
	v_exp_f32_e32 v145, v145
	v_exp_f32_e32 v146, v146
	v_exp_f32_e32 v147, v147
	s_waitcnt lgkmcnt(2)
	v_mfma_f32_32x32x16_bf16 v[128:143], v[226:229], v[188:191], 0
	v_mfma_f32_32x32x16_bf16 v[128:143], v[230:233], v[184:187], v[128:143]
	ds_read_b128 v[226:229], v202 offset:16384
	ds_read_b128 v[230:233], v203 offset:16384
	s_mov_b32 m0, s24
	s_nop 0
	global_load_lds_dwordx4 v220, s[86:87] sc1
	v_exp_f32_e32 v148, v148
	v_exp_f32_e32 v149, v149
	v_exp_f32_e32 v150, v150
	v_exp_f32_e32 v151, v151
	v_add_f32_e32 v246, v144, v145
	v_add_f32_e32 v246, v146, v246
	v_add_f32_e32 v246, v147, v246
	s_waitcnt lgkmcnt(2)
	v_mfma_f32_32x32x16_bf16 v[128:143], v[234:237], v[180:183], v[128:143]
	v_mfma_f32_32x32x16_bf16 v[128:143], v[238:241], v[176:179], v[128:143]
	ds_read_b128 v[234:237], v204 offset:16384
	ds_read_b128 v[238:241], v205 offset:16384
	s_add_i32 m0, s24, 0x2000
	s_nop 0
	global_load_lds_dwordx4 v219, s[86:87] sc1
	v_exp_f32_e32 v152, v152
	v_exp_f32_e32 v153, v153
	v_exp_f32_e32 v154, v154
	v_exp_f32_e32 v155, v155
	v_add_f32_e32 v246, v148, v246
	v_add_f32_e32 v246, v149, v246
	v_add_f32_e32 v246, v150, v246
	v_add_f32_e32 v246, v151, v246
	s_waitcnt lgkmcnt(2)
	v_mfma_f32_32x32x16_bf16 v[128:143], v[226:229], v[172:175], v[128:143]
	v_mfma_f32_32x32x16_bf16 v[128:143], v[230:233], v[168:171], v[128:143]
	v_exp_f32_e32 v156, v156
	v_exp_f32_e32 v157, v157
	v_exp_f32_e32 v158, v158
	v_exp_f32_e32 v159, v159
	v_add_f32_e32 v246, v152, v246
	v_add_f32_e32 v246, v153, v246
	v_add_f32_e32 v246, v154, v246
	v_add_f32_e32 v246, v155, v246
	v_cvt_pk_bf16_f32 v226, v144, v145
	v_cvt_pk_bf16_f32 v227, v146, v147
	v_cvt_pk_bf16_f32 v228, v148, v149
	v_cvt_pk_bf16_f32 v229, v150, v151
	s_waitcnt lgkmcnt(0)
	v_mfma_f32_32x32x16_bf16 v[128:143], v[234:237], v[164:167], v[128:143]
	v_mfma_f32_32x32x16_bf16 v[128:143], v[238:241], v[160:163], v[128:143]
	v_add_u32_e32 v245, s84, v214
	s_add_i32 s85, s84, 0x8000
	s_cmp_eq_u32 s85, 0x18000
	s_cselect_b32 s85, 0, s85
	ds_read_b64_tr_b16 v[234:235], v245 offset:0
	ds_read_b64_tr_b16 v[236:237], v245 offset:2048
	ds_read_b64_tr_b16 v[238:239], v245 offset:512
	ds_read_b64_tr_b16 v[240:241], v245 offset:2560
	ds_read_b64_tr_b16 v[144:145], v245 offset:4096
	ds_read_b64_tr_b16 v[146:147], v245 offset:6144
	ds_read_b64_tr_b16 v[148:149], v245 offset:4608
	ds_read_b64_tr_b16 v[150:151], v245 offset:6656
	v_add_f32_e32 v246, v156, v246
	v_add_f32_e32 v246, v157, v246
	v_add_f32_e32 v246, v158, v246
	v_add_f32_e32 v246, v159, v246
	v_cvt_pk_bf16_f32 v230, v152, v153
	v_cvt_pk_bf16_f32 v231, v154, v155
	v_cvt_pk_bf16_f32 v232, v156, v157
	v_cvt_pk_bf16_f32 v233, v158, v159
	v_add_f32_e32 v215, v215, v246
	ds_read_b64_tr_b16 v[152:153], v245 offset:1024
	ds_read_b64_tr_b16 v[154:155], v245 offset:3072
	ds_read_b64_tr_b16 v[156:157], v245 offset:1536
	ds_read_b64_tr_b16 v[158:159], v245 offset:3584
	s_waitcnt lgkmcnt(8)
	v_mfma_f32_32x32x16_bf16 v[112:127], v[226:229], v[234:237], v[112:127]
	v_mfma_f32_32x32x16_bf16 v[96:111], v[226:229], v[238:241], v[96:111]
	ds_read_b64_tr_b16 v[234:235], v245 offset:5120
	ds_read_b64_tr_b16 v[236:237], v245 offset:7168
	ds_read_b64_tr_b16 v[238:239], v245 offset:5632
	ds_read_b64_tr_b16 v[240:241], v245 offset:7680
	s_add_i32 s41, s85, s24
	s_add_i32 m0, s41, 0x8000
	s_nop 0
	global_load_lds_dwordx4 v218, s[2:3] sc1
	s_waitcnt lgkmcnt(8)
	v_mfma_f32_32x32x16_bf16 v[112:127], v[230:233], v[144:147], v[112:127]
	v_mfma_f32_32x32x16_bf16 v[96:111], v[230:233], v[148:151], v[96:111]
	ds_read_b64_tr_b16 v[144:145], v245 offset:16384
	ds_read_b64_tr_b16 v[146:147], v245 offset:18432
	ds_read_b64_tr_b16 v[148:149], v245 offset:16896
	ds_read_b64_tr_b16 v[150:151], v245 offset:18944
	s_add_i32 s41, s85, s24
	s_add_i32 m0, s41, 0xa000
	s_nop 0
	global_load_lds_dwordx4 v217, s[2:3] sc1
	s_waitcnt lgkmcnt(8)
	v_mfma_f32_32x32x16_bf16 v[80:95], v[226:229], v[152:155], v[80:95]
	v_mfma_f32_32x32x16_bf16 v[64:79], v[226:229], v[156:159], v[64:79]
	ds_read_b64_tr_b16 v[152:153], v245 offset:20480
	ds_read_b64_tr_b16 v[154:155], v245 offset:22528
	ds_read_b64_tr_b16 v[156:157], v245 offset:20992
	ds_read_b64_tr_b16 v[158:159], v245 offset:23040
	s_add_i32 s41, s85, s24
	s_add_i32 m0, s41, 0xc000
	s_nop 0
	global_load_lds_dwordx4 v242, s[2:3] sc1
	s_waitcnt lgkmcnt(8)
	v_mfma_f32_32x32x16_bf16 v[80:95], v[230:233], v[234:237], v[80:95]
	v_mfma_f32_32x32x16_bf16 v[64:79], v[230:233], v[238:241], v[64:79]
	ds_read_b64_tr_b16 v[234:235], v245 offset:17408
	ds_read_b64_tr_b16 v[236:237], v245 offset:19456
	ds_read_b64_tr_b16 v[238:239], v245 offset:17920
	ds_read_b64_tr_b16 v[240:241], v245 offset:19968
	s_add_i32 s41, s85, s24
	s_add_i32 m0, s41, 0xe000
	s_nop 0
	global_load_lds_dwordx4 v243, s[2:3] sc1
	s_waitcnt lgkmcnt(8)
	v_mfma_f32_32x32x16_bf16 v[48:63], v[226:229], v[144:147], v[48:63]
	v_mfma_f32_32x32x16_bf16 v[32:47], v[226:229], v[148:151], v[32:47]
	ds_read_b64_tr_b16 v[144:145], v245 offset:21504
	ds_read_b64_tr_b16 v[146:147], v245 offset:23552
	ds_read_b64_tr_b16 v[148:149], v245 offset:22016
	ds_read_b64_tr_b16 v[150:151], v245 offset:24064
	s_waitcnt lgkmcnt(8)
	v_mfma_f32_32x32x16_bf16 v[48:63], v[230:233], v[152:155], v[48:63]
	v_mfma_f32_32x32x16_bf16 v[32:47], v[230:233], v[156:159], v[32:47]
	s_waitcnt lgkmcnt(0)
	v_mfma_f32_32x32x16_bf16 v[16:31], v[226:229], v[234:237], v[16:31]
	s_waitcnt vmcnt(0)
	s_barrier
; #define SBAR() __builtin_amdgcn_sched_barrier(0)
; #define PVR(S, DA, DB, vbase) do { S[0] = tr_read<v_rd_off(DA, 0, 0)>(vbase); S[1] = tr_read<v_rd_off(DA, 0, 1)>(vbase); S[2] = tr_read<v_rd_off(DB, 0, 0)>(vbase); S[3] = tr_read<v_rd_off(DB, 0, 1)>(vbase); \
;     S[4] = tr_read<v_rd_off(DA, 1, 0)>(vbase); S[5] = tr_read<v_rd_off(DA, 1, 1)>(vbase); S[6] = tr_read<v_rd_off(DB, 1, 0)>(vbase); S[7] = tr_read<v_rd_off(DB, 1, 1)>(vbase); } while (0)
; #define RAWBAR() do { asm volatile("s_waitcnt lgkmcnt(0)" ::: "memory"); __builtin_amdgcn_s_barrier(); asm volatile("" ::: "memory"); } while (0)
; #define RAWBAR() do { asm volatile("s_waitcnt lgkmcnt(0)" ::: "memory"); __builtin_amdgcn_s_barrier(); asm volatile("" ::: "memory"); } while (0)
; #define RAWBAR() do { asm volatile("s_waitcnt lgkmcnt(0)" ::: "memory"); __builtin_amdgcn_s_barrier(); asm volatile("" ::: "memory"); } while (0)
; #define RAWBAR() do { asm volatile("s_waitcnt lgkmcnt(0)" ::: "memory"); __builtin_amdgcn_s_barrier(); asm volatile("" ::: "memory"); } while (0)
; #define RAWBAR() do { asm volatile("s_waitcnt lgkmcnt(0)" ::: "memory"); __builtin_amdgcn_s_barrier(); asm volatile("" ::: "memory"); } while (0)
; template <int MODE> ...
;     ...
;   for (int j = 0; j < NT; ++j) {
;     const int buf = j & 1;
;     if (j + 1 < NT) { STAGE((j + 1) * KVBLK, buf ^ 1); }
;     const char* Kb = K_lds + buf * 16384;
;     f32x16 pe = {}, po = {};
; #pragma unroll
;     for (int d0 = 0; d0 < 8; d0 += 2) {
;       const bf16x8 k0 = *reinterpret_cast<const bf16x8*>(Kb + KSWZ(krow, (d0 * 16 + hi * 8) * 2));
;       const bf16x8 k1 = *reinterpret_cast<const bf16x8*>(Kb + KSWZ(krow, ((d0 + 1) * 16 + hi * 8) * 2));
;       pe = __builtin_amdgcn_mfma_f32_32x32x16_bf16(k0, qr[d0], pe, 0, 0, 0);
;       po = __builtin_amdgcn_mfma_f32_32x32x16_bf16(k1, qr[d0 + 1], po, 0, 0, 0); }
;     const int vo = vb0 + buf * 32768;
;     s16x4 R0_[8], R1_[8];
;     PVR(R0_, 0, 1, vo);
;     f32x16 p;
; #pragma unroll
;     for (int r = 0; r < 16; ++r) p[r] = __builtin_amdgcn_exp2f(fmaf(pe[r] + po[r], C, negMc));
;     float ps = 0.f;
; #pragma unroll
;     for (int r = 0; r < 16; ++r) ps += p[r];
;     lsum += ps;
;     const bf16x8 own0 = pk8(p, 0), own1 = pk8(p, 8);
;     SBAR();
;     PV_TAIL4(o, vo, vo + 16384, own0, own1);
;     asm volatile("s_waitcnt vmcnt(0)" ::: "memory");
;     RAWBAR();
;   }
	s_add_u32 s86, s86, 0x4000
	s_addc_u32 s87, s87, 0
	s_add_u32 s2, s2, 0x8000
	s_addc_u32 s3, s3, 0
	v_mfma_f32_32x32x16_bf16 v[0:15], v[226:229], v[238:241], v[0:15]
	v_mfma_f32_32x32x16_bf16 v[16:31], v[230:233], v[144:147], v[16:31]
	s_add_i32 s84, s84, 0x8000
	s_cmp_eq_u32 s84, 0x18000
	s_cselect_b32 s84, 0, s84
	v_mfma_f32_32x32x16_bf16 v[0:15], v[230:233], v[148:151], v[0:15]
	ds_read_b128 v[226:229], v225 offset:0
	ds_read_b128 v[230:233], v223 offset:0
	ds_read_b128 v[234:237], v222 offset:0
	ds_read_b128 v[238:241], v221 offset:0
	v_exp_f32_e32 v128, v128
	v_exp_f32_e32 v129, v129
	v_exp_f32_e32 v130, v130
	v_exp_f32_e32 v131, v131
	s_waitcnt lgkmcnt(2)
	v_mfma_f32_32x32x16_bf16 v[144:159], v[226:229], v[188:191], 0
	v_mfma_f32_32x32x16_bf16 v[144:159], v[230:233], v[184:187], v[144:159]
	ds_read_b128 v[226:229], v202 offset:0
	ds_read_b128 v[230:233], v203 offset:0
	s_add_i32 m0, s24, 0x4000
	s_nop 0
	global_load_lds_dwordx4 v220, s[86:87] sc1
	v_exp_f32_e32 v132, v132
	v_exp_f32_e32 v133, v133
	v_exp_f32_e32 v134, v134
	v_exp_f32_e32 v135, v135
	v_add_f32_e32 v246, v128, v129
	v_add_f32_e32 v246, v130, v246
	v_add_f32_e32 v246, v131, v246
	s_waitcnt lgkmcnt(2)
	v_mfma_f32_32x32x16_bf16 v[144:159], v[234:237], v[180:183], v[144:159]
	v_mfma_f32_32x32x16_bf16 v[144:159], v[238:241], v[176:179], v[144:159]
	ds_read_b128 v[234:237], v204 offset:0
	ds_read_b128 v[238:241], v205 offset:0
	s_add_i32 m0, s24, 0x6000
	s_nop 0
	global_load_lds_dwordx4 v219, s[86:87] sc1
	v_exp_f32_e32 v136, v136
	v_exp_f32_e32 v137, v137
	v_exp_f32_e32 v138, v138
	v_exp_f32_e32 v139, v139
	v_add_f32_e32 v246, v132, v246
	v_add_f32_e32 v246, v133, v246
	v_add_f32_e32 v246, v134, v246
	v_add_f32_e32 v246, v135, v246
	s_waitcnt lgkmcnt(2)
	v_mfma_f32_32x32x16_bf16 v[144:159], v[226:229], v[172:175], v[144:159]
	v_mfma_f32_32x32x16_bf16 v[144:159], v[230:233], v[168:171], v[144:159]
	v_exp_f32_e32 v140, v140
	v_exp_f32_e32 v141, v141
	v_exp_f32_e32 v142, v142
	v_exp_f32_e32 v143, v143
	v_add_f32_e32 v246, v136, v246
	v_add_f32_e32 v246, v137, v246
	v_add_f32_e32 v246, v138, v246
	v_add_f32_e32 v246, v139, v246
	v_cvt_pk_bf16_f32 v226, v128, v129
	v_cvt_pk_bf16_f32 v227, v130, v131
	v_cvt_pk_bf16_f32 v228, v132, v133
	v_cvt_pk_bf16_f32 v229, v134, v135
	s_waitcnt lgkmcnt(0)
	v_mfma_f32_32x32x16_bf16 v[144:159], v[234:237], v[164:167], v[144:159]
	v_mfma_f32_32x32x16_bf16 v[144:159], v[238:241], v[160:163], v[144:159]
	v_add_u32_e32 v245, s84, v214
	s_add_i32 s85, s84, 0x8000
	s_cmp_eq_u32 s85, 0x18000
	s_cselect_b32 s85, 0, s85
	ds_read_b64_tr_b16 v[234:235], v245 offset:0
	ds_read_b64_tr_b16 v[236:237], v245 offset:2048
	ds_read_b64_tr_b16 v[238:239], v245 offset:512
	ds_read_b64_tr_b16 v[240:241], v245 offset:2560
	ds_read_b64_tr_b16 v[128:129], v245 offset:4096
	ds_read_b64_tr_b16 v[130:131], v245 offset:6144
	ds_read_b64_tr_b16 v[132:133], v245 offset:4608
	ds_read_b64_tr_b16 v[134:135], v245 offset:6656
	v_add_f32_e32 v246, v140, v246
	v_add_f32_e32 v246, v141, v246
	v_add_f32_e32 v246, v142, v246
	v_add_f32_e32 v246, v143, v246
	v_cvt_pk_bf16_f32 v230, v136, v137
	v_cvt_pk_bf16_f32 v231, v138, v139
	v_cvt_pk_bf16_f32 v232, v140, v141
	v_cvt_pk_bf16_f32 v233, v142, v143
	v_add_f32_e32 v215, v215, v246
	ds_read_b64_tr_b16 v[136:137], v245 offset:1024
	ds_read_b64_tr_b16 v[138:139], v245 offset:3072
	ds_read_b64_tr_b16 v[140:141], v245 offset:1536
	ds_read_b64_tr_b16 v[142:143], v245 offset:3584
	s_waitcnt lgkmcnt(8)
	v_mfma_f32_32x32x16_bf16 v[112:127], v[226:229], v[234:237], v[112:127]
	v_mfma_f32_32x32x16_bf16 v[96:111], v[226:229], v[238:241], v[96:111]
	ds_read_b64_tr_b16 v[234:235], v245 offset:5120
	ds_read_b64_tr_b16 v[236:237], v245 offset:7168
	ds_read_b64_tr_b16 v[238:239], v245 offset:5632
	ds_read_b64_tr_b16 v[240:241], v245 offset:7680
	s_add_i32 s41, s85, s24
	s_add_i32 m0, s41, 0x8000
	s_nop 0
	global_load_lds_dwordx4 v218, s[2:3] sc1
	s_waitcnt lgkmcnt(8)
	v_mfma_f32_32x32x16_bf16 v[112:127], v[230:233], v[128:131], v[112:127]
	v_mfma_f32_32x32x16_bf16 v[96:111], v[230:233], v[132:135], v[96:111]
	ds_read_b64_tr_b16 v[128:129], v245 offset:16384
	ds_read_b64_tr_b16 v[130:131], v245 offset:18432
	ds_read_b64_tr_b16 v[132:133], v245 offset:16896
	ds_read_b64_tr_b16 v[134:135], v245 offset:18944
	s_add_i32 s41, s85, s24
	s_add_i32 m0, s41, 0xa000
	s_nop 0
	global_load_lds_dwordx4 v217, s[2:3] sc1
	s_waitcnt lgkmcnt(8)
	v_mfma_f32_32x32x16_bf16 v[80:95], v[226:229], v[136:139], v[80:95]
	v_mfma_f32_32x32x16_bf16 v[64:79], v[226:229], v[140:143], v[64:79]
	ds_read_b64_tr_b16 v[136:137], v245 offset:20480
	ds_read_b64_tr_b16 v[138:139], v245 offset:22528
	ds_read_b64_tr_b16 v[140:141], v245 offset:20992
	ds_read_b64_tr_b16 v[142:143], v245 offset:23040
	s_add_i32 s41, s85, s24
	s_add_i32 m0, s41, 0xc000
	s_nop 0
	global_load_lds_dwordx4 v242, s[2:3] sc1
	s_waitcnt lgkmcnt(8)
	v_mfma_f32_32x32x16_bf16 v[80:95], v[230:233], v[234:237], v[80:95]
	v_mfma_f32_32x32x16_bf16 v[64:79], v[230:233], v[238:241], v[64:79]
	ds_read_b64_tr_b16 v[234:235], v245 offset:17408
	ds_read_b64_tr_b16 v[236:237], v245 offset:19456
	ds_read_b64_tr_b16 v[238:239], v245 offset:17920
	ds_read_b64_tr_b16 v[240:241], v245 offset:19968
	s_add_i32 s41, s85, s24
	s_add_i32 m0, s41, 0xe000
	s_nop 0
	global_load_lds_dwordx4 v243, s[2:3] sc1
	s_waitcnt lgkmcnt(8)
	v_mfma_f32_32x32x16_bf16 v[48:63], v[226:229], v[128:131], v[48:63]
	v_mfma_f32_32x32x16_bf16 v[32:47], v[226:229], v[132:135], v[32:47]
	ds_read_b64_tr_b16 v[128:129], v245 offset:21504
	ds_read_b64_tr_b16 v[130:131], v245 offset:23552
	ds_read_b64_tr_b16 v[132:133], v245 offset:22016
	ds_read_b64_tr_b16 v[134:135], v245 offset:24064
	s_waitcnt lgkmcnt(8)
	v_mfma_f32_32x32x16_bf16 v[48:63], v[230:233], v[136:139], v[48:63]
	v_mfma_f32_32x32x16_bf16 v[32:47], v[230:233], v[140:143], v[32:47]
	s_waitcnt lgkmcnt(0)
	v_mfma_f32_32x32x16_bf16 v[16:31], v[226:229], v[234:237], v[16:31]
	s_waitcnt vmcnt(0)
	s_barrier
	s_add_u32 s86, s86, 0x4000
	s_addc_u32 s87, s87, 0
	s_add_u32 s2, s2, 0x8000
	s_addc_u32 s3, s3, 0
	v_mfma_f32_32x32x16_bf16 v[0:15], v[226:229], v[238:241], v[0:15]
	v_mfma_f32_32x32x16_bf16 v[16:31], v[230:233], v[128:131], v[16:31]
	s_add_i32 s84, s84, 0x8000
	s_cmp_eq_u32 s84, 0x18000
	s_cselect_b32 s84, 0, s84
	s_add_i32 s25, s25, 1
	s_cmpk_eq_i32 s25, 0x82
	v_mfma_f32_32x32x16_bf16 v[0:15], v[230:233], v[132:135], v[0:15]
	s_cbranch_scc0 .LBB0_1019
	s_barrier
	s_branch .Lattn_join_m0

; #define SBAR() __builtin_amdgcn_sched_barrier(0)
; #define PVR(S, DA, DB, vbase) do { S[0] = tr_read<v_rd_off(DA, 0, 0)>(vbase); S[1] = tr_read<v_rd_off(DA, 0, 1)>(vbase); S[2] = tr_read<v_rd_off(DB, 0, 0)>(vbase); S[3] = tr_read<v_rd_off(DB, 0, 1)>(vbase); \
;     S[4] = tr_read<v_rd_off(DA, 1, 0)>(vbase); S[5] = tr_read<v_rd_off(DA, 1, 1)>(vbase); S[6] = tr_read<v_rd_off(DB, 1, 0)>(vbase); S[7] = tr_read<v_rd_off(DB, 1, 1)>(vbase); } while (0)
; #define RAWBAR() do { asm volatile("s_waitcnt lgkmcnt(0)" ::: "memory"); __builtin_amdgcn_s_barrier(); asm volatile("" ::: "memory"); } while (0)
; #define RAWBAR() do { asm volatile("s_waitcnt lgkmcnt(0)" ::: "memory"); __builtin_amdgcn_s_barrier(); asm volatile("" ::: "memory"); } while (0)
; #define RAWBAR() do { asm volatile("s_waitcnt lgkmcnt(0)" ::: "memory"); __builtin_amdgcn_s_barrier(); asm volatile("" ::: "memory"); } while (0)
; #define RAWBAR() do { asm volatile("s_waitcnt lgkmcnt(0)" ::: "memory"); __builtin_amdgcn_s_barrier(); asm volatile("" ::: "memory"); } while (0)
; #define RAWBAR() do { asm volatile("s_waitcnt lgkmcnt(0)" ::: "memory"); __builtin_amdgcn_s_barrier(); asm volatile("" ::: "memory"); } while (0)
; template <int MODE> ...
;     ...
;   for (int j = 0; j < NT; ++j) {
;     const int buf = j & 1;
;     if (j + 1 < NT) { STAGE((j + 1) * KVBLK, buf ^ 1); }
;     const char* Kb = K_lds + buf * 16384;
;     f32x16 pe = {}, po = {};
; #pragma unroll
;     for (int d0 = 0; d0 < 8; d0 += 2) {
;       const bf16x8 k0 = *reinterpret_cast<const bf16x8*>(Kb + KSWZ(krow, (d0 * 16 + hi * 8) * 2));
;       const bf16x8 k1 = *reinterpret_cast<const bf16x8*>(Kb + KSWZ(krow, ((d0 + 1) * 16 + hi * 8) * 2));
;       pe = __builtin_amdgcn_mfma_f32_32x32x16_bf16(k0, qr[d0], pe, 0, 0, 0);
;       po = __builtin_amdgcn_mfma_f32_32x32x16_bf16(k1, qr[d0 + 1], po, 0, 0, 0); }
;     const int vo = vb0 + buf * 32768;
;     s16x4 R0_[8], R1_[8];
;     PVR(R0_, 0, 1, vo);
;     f32x16 p;
; #pragma unroll
;     for (int r = 0; r < 16; ++r) p[r] = __builtin_amdgcn_exp2f(fmaf(pe[r] + po[r], C, negMc));
;     float ps = 0.f;
; #pragma unroll
;     for (int r = 0; r < 16; ++r) ps += p[r];
;     lsum += ps;
;     const bf16x8 own0 = pk8(p, 0), own1 = pk8(p, 8);
;     SBAR();
;     PV_TAIL4(o, vo, vo + 16384, own0, own1);
;     asm volatile("s_waitcnt vmcnt(0)" ::: "memory");
;     RAWBAR();
;   }
.LattnB_m0:
	ds_read_b128 v[226:229], v225 offset:16384
	ds_read_b128 v[230:233], v223 offset:16384
	ds_read_b128 v[234:237], v222 offset:16384
	ds_read_b128 v[238:241], v221 offset:16384
	v_exp_f32_e32 v144, v144
	v_exp_f32_e32 v145, v145
	v_exp_f32_e32 v146, v146
	v_exp_f32_e32 v147, v147
	s_waitcnt lgkmcnt(2)
	v_mfma_f32_32x32x16_bf16 v[128:143], v[226:229], v[188:191], 0
	v_mfma_f32_32x32x16_bf16 v[128:143], v[230:233], v[184:187], v[128:143]
	ds_read_b128 v[226:229], v202 offset:16384
	ds_read_b128 v[230:233], v203 offset:16384
	v_exp_f32_e32 v148, v148
	v_exp_f32_e32 v149, v149
	v_exp_f32_e32 v150, v150
	v_exp_f32_e32 v151, v151
	v_add_f32_e32 v246, v144, v145
	v_add_f32_e32 v246, v146, v246
	v_add_f32_e32 v246, v147, v246
	s_waitcnt lgkmcnt(2)
	v_mfma_f32_32x32x16_bf16 v[128:143], v[234:237], v[180:183], v[128:143]
	v_mfma_f32_32x32x16_bf16 v[128:143], v[238:241], v[176:179], v[128:143]
	ds_read_b128 v[234:237], v204 offset:16384
	ds_read_b128 v[238:241], v205 offset:16384
	v_exp_f32_e32 v152, v152
	v_exp_f32_e32 v153, v153
	v_exp_f32_e32 v154, v154
	v_exp_f32_e32 v155, v155
	v_add_f32_e32 v246, v148, v246
	v_add_f32_e32 v246, v149, v246
	v_add_f32_e32 v246, v150, v246
	v_add_f32_e32 v246, v151, v246
	s_waitcnt lgkmcnt(2)
	v_mfma_f32_32x32x16_bf16 v[128:143], v[226:229], v[172:175], v[128:143]
	v_mfma_f32_32x32x16_bf16 v[128:143], v[230:233], v[168:171], v[128:143]
	v_exp_f32_e32 v156, v156
	v_exp_f32_e32 v157, v157
	v_exp_f32_e32 v158, v158
	v_exp_f32_e32 v159, v159
	v_add_f32_e32 v246, v152, v246
	v_add_f32_e32 v246, v153, v246
	v_add_f32_e32 v246, v154, v246
	v_add_f32_e32 v246, v155, v246
	v_cvt_pk_bf16_f32 v226, v144, v145
	v_cvt_pk_bf16_f32 v227, v146, v147
	v_cvt_pk_bf16_f32 v228, v148, v149
	v_cvt_pk_bf16_f32 v229, v150, v151
	s_waitcnt lgkmcnt(0)
	v_mfma_f32_32x32x16_bf16 v[128:143], v[234:237], v[164:167], v[128:143]
	v_mfma_f32_32x32x16_bf16 v[128:143], v[238:241], v[160:163], v[128:143]
	s_waitcnt vmcnt(0)
	s_barrier
	s_add_u32 s86, s86, 0x4000
	s_addc_u32 s87, s87, 0
	s_add_u32 s2, s2, 0x8000
	s_addc_u32 s3, s3, 0
	v_add_u32_e32 v245, s84, v214
	s_sub_u32 s85, s84, 0x8000
	s_cmp_eq_u32 s84, 0
	s_cselect_b32 s85, 0x10000, s85
	ds_read_b64_tr_b16 v[234:235], v245 offset:0
	ds_read_b64_tr_b16 v[236:237], v245 offset:2048
	ds_read_b64_tr_b16 v[238:239], v245 offset:512
	ds_read_b64_tr_b16 v[240:241], v245 offset:2560
	ds_read_b64_tr_b16 v[144:145], v245 offset:4096
	ds_read_b64_tr_b16 v[146:147], v245 offset:6144
	ds_read_b64_tr_b16 v[148:149], v245 offset:4608
	ds_read_b64_tr_b16 v[150:151], v245 offset:6656
	v_add_f32_e32 v246, v156, v246
	v_add_f32_e32 v246, v157, v246
	v_add_f32_e32 v246, v158, v246
	v_add_f32_e32 v246, v159, v246
	v_cvt_pk_bf16_f32 v230, v152, v153
	v_cvt_pk_bf16_f32 v231, v154, v155
	v_cvt_pk_bf16_f32 v232, v156, v157
	v_cvt_pk_bf16_f32 v233, v158, v159
	v_add_f32_e32 v215, v215, v246
	ds_read_b64_tr_b16 v[152:153], v245 offset:1024
	ds_read_b64_tr_b16 v[154:155], v245 offset:3072
	ds_read_b64_tr_b16 v[156:157], v245 offset:1536
	ds_read_b64_tr_b16 v[158:159], v245 offset:3584
	s_waitcnt lgkmcnt(8)
	v_mfma_f32_32x32x16_bf16 v[112:127], v[226:229], v[234:237], v[112:127]
	v_mfma_f32_32x32x16_bf16 v[96:111], v[226:229], v[238:241], v[96:111]
	ds_read_b64_tr_b16 v[234:235], v245 offset:5120
	ds_read_b64_tr_b16 v[236:237], v245 offset:7168
	ds_read_b64_tr_b16 v[238:239], v245 offset:5632
	ds_read_b64_tr_b16 v[240:241], v245 offset:7680
	s_add_i32 s41, s85, s24
	s_add_i32 m0, s41, 0x8000
	s_nop 0
	global_load_lds_dwordx4 v218, s[2:3] sc1
	s_waitcnt lgkmcnt(8)
	v_mfma_f32_32x32x16_bf16 v[112:127], v[230:233], v[144:147], v[112:127]
	v_mfma_f32_32x32x16_bf16 v[96:111], v[230:233], v[148:151], v[96:111]
	ds_read_b64_tr_b16 v[144:145], v245 offset:16384
	ds_read_b64_tr_b16 v[146:147], v245 offset:18432
	ds_read_b64_tr_b16 v[148:149], v245 offset:16896
	ds_read_b64_tr_b16 v[150:151], v245 offset:18944
	s_add_i32 s41, s85, s24
	s_add_i32 m0, s41, 0xa000
	s_nop 0
	global_load_lds_dwordx4 v217, s[2:3] sc1
	s_waitcnt lgkmcnt(8)
	v_mfma_f32_32x32x16_bf16 v[80:95], v[226:229], v[152:155], v[80:95]
	v_mfma_f32_32x32x16_bf16 v[64:79], v[226:229], v[156:159], v[64:79]
	ds_read_b64_tr_b16 v[152:153], v245 offset:20480
	ds_read_b64_tr_b16 v[154:155], v245 offset:22528
	ds_read_b64_tr_b16 v[156:157], v245 offset:20992
	ds_read_b64_tr_b16 v[158:159], v245 offset:23040
	s_add_i32 s41, s85, s24
	s_add_i32 m0, s41, 0xc000
	s_nop 0
	global_load_lds_dwordx4 v242, s[2:3] sc1
	s_waitcnt lgkmcnt(8)
	v_mfma_f32_32x32x16_bf16 v[80:95], v[230:233], v[234:237], v[80:95]
	v_mfma_f32_32x32x16_bf16 v[64:79], v[230:233], v[238:241], v[64:79]
	ds_read_b64_tr_b16 v[234:235], v245 offset:17408
	ds_read_b64_tr_b16 v[236:237], v245 offset:19456
	ds_read_b64_tr_b16 v[238:239], v245 offset:17920
	ds_read_b64_tr_b16 v[240:241], v245 offset:19968
	s_add_i32 s41, s85, s24
	s_add_i32 m0, s41, 0xe000
	s_nop 0
	global_load_lds_dwordx4 v243, s[2:3] sc1
	s_waitcnt lgkmcnt(8)
	v_mfma_f32_32x32x16_bf16 v[48:63], v[226:229], v[144:147], v[48:63]
	v_mfma_f32_32x32x16_bf16 v[32:47], v[226:229], v[148:151], v[32:47]
	ds_read_b64_tr_b16 v[144:145], v245 offset:21504
	ds_read_b64_tr_b16 v[146:147], v245 offset:23552
	ds_read_b64_tr_b16 v[148:149], v245 offset:22016
	ds_read_b64_tr_b16 v[150:151], v245 offset:24064
	s_add_i32 m0, s24, 0x4000
	s_nop 0
	global_load_lds_dwordx4 v220, s[86:87] sc1
	s_waitcnt lgkmcnt(8)
	v_mfma_f32_32x32x16_bf16 v[48:63], v[230:233], v[152:155], v[48:63]
	v_mfma_f32_32x32x16_bf16 v[32:47], v[230:233], v[156:159], v[32:47]
	s_add_i32 m0, s24, 0x6000
	s_nop 0
	global_load_lds_dwordx4 v219, s[86:87] sc1
	s_waitcnt lgkmcnt(0)
; #define SBAR() __builtin_amdgcn_sched_barrier(0)
; #define PVR(S, DA, DB, vbase) do { S[0] = tr_read<v_rd_off(DA, 0, 0)>(vbase); S[1] = tr_read<v_rd_off(DA, 0, 1)>(vbase); S[2] = tr_read<v_rd_off(DB, 0, 0)>(vbase); S[3] = tr_read<v_rd_off(DB, 0, 1)>(vbase); \
;     S[4] = tr_read<v_rd_off(DA, 1, 0)>(vbase); S[5] = tr_read<v_rd_off(DA, 1, 1)>(vbase); S[6] = tr_read<v_rd_off(DB, 1, 0)>(vbase); S[7] = tr_read<v_rd_off(DB, 1, 1)>(vbase); } while (0)
; #define RAWBAR() do { asm volatile("s_waitcnt lgkmcnt(0)" ::: "memory"); __builtin_amdgcn_s_barrier(); asm volatile("" ::: "memory"); } while (0)
; #define RAWBAR() do { asm volatile("s_waitcnt lgkmcnt(0)" ::: "memory"); __builtin_amdgcn_s_barrier(); asm volatile("" ::: "memory"); } while (0)
; #define RAWBAR() do { asm volatile("s_waitcnt lgkmcnt(0)" ::: "memory"); __builtin_amdgcn_s_barrier(); asm volatile("" ::: "memory"); } while (0)
; #define RAWBAR() do { asm volatile("s_waitcnt lgkmcnt(0)" ::: "memory"); __builtin_amdgcn_s_barrier(); asm volatile("" ::: "memory"); } while (0)
; #define RAWBAR() do { asm volatile("s_waitcnt lgkmcnt(0)" ::: "memory"); __builtin_amdgcn_s_barrier(); asm volatile("" ::: "memory"); } while (0)
; template <int MODE> ...
;     ...
;   for (int j = 0; j < NT; ++j) {
;     const int buf = j & 1;
;     if (j + 1 < NT) { STAGE((j + 1) * KVBLK, buf ^ 1); }
;     const char* Kb = K_lds + buf * 16384;
;     f32x16 pe = {}, po = {};
; #pragma unroll
;     for (int d0 = 0; d0 < 8; d0 += 2) {
;       const bf16x8 k0 = *reinterpret_cast<const bf16x8*>(Kb + KSWZ(krow, (d0 * 16 + hi * 8) * 2));
;       const bf16x8 k1 = *reinterpret_cast<const bf16x8*>(Kb + KSWZ(krow, ((d0 + 1) * 16 + hi * 8) * 2));
;       pe = __builtin_amdgcn_mfma_f32_32x32x16_bf16(k0, qr[d0], pe, 0, 0, 0);
;       po = __builtin_amdgcn_mfma_f32_32x32x16_bf16(k1, qr[d0 + 1], po, 0, 0, 0); }
;     const int vo = vb0 + buf * 32768;
;     s16x4 R0_[8], R1_[8];
;     PVR(R0_, 0, 1, vo);
;     f32x16 p;
; #pragma unroll
;     for (int r = 0; r < 16; ++r) p[r] = __builtin_amdgcn_exp2f(fmaf(pe[r] + po[r], C, negMc));
;     float ps = 0.f;
; #pragma unroll
;     for (int r = 0; r < 16; ++r) ps += p[r];
;     lsum += ps;
;     const bf16x8 own0 = pk8(p, 0), own1 = pk8(p, 8);
;     SBAR();
;     PV_TAIL4(o, vo, vo + 16384, own0, own1);
;     asm volatile("s_waitcnt vmcnt(0)" ::: "memory");
;     RAWBAR();
;   }
	v_mfma_f32_32x32x16_bf16 v[16:31], v[226:229], v[234:237], v[16:31]
	v_mfma_f32_32x32x16_bf16 v[0:15], v[226:229], v[238:241], v[0:15]
	v_mfma_f32_32x32x16_bf16 v[16:31], v[230:233], v[144:147], v[16:31]
	s_add_i32 s84, s84, 0x8000
	s_cmp_eq_u32 s84, 0x18000
	s_cselect_b32 s84, 0, s84
	v_mfma_f32_32x32x16_bf16 v[0:15], v[230:233], v[148:151], v[0:15]
	ds_read_b128 v[226:229], v225 offset:0
	ds_read_b128 v[230:233], v223 offset:0
	ds_read_b128 v[234:237], v222 offset:0
	ds_read_b128 v[238:241], v221 offset:0
	v_exp_f32_e32 v128, v128
	v_exp_f32_e32 v129, v129
	v_exp_f32_e32 v130, v130
	v_exp_f32_e32 v131, v131
	s_waitcnt lgkmcnt(2)
	v_mfma_f32_32x32x16_bf16 v[144:159], v[226:229], v[188:191], 0
	v_mfma_f32_32x32x16_bf16 v[144:159], v[230:233], v[184:187], v[144:159]
	ds_read_b128 v[226:229], v202 offset:0
	ds_read_b128 v[230:233], v203 offset:0
	v_exp_f32_e32 v132, v132
	v_exp_f32_e32 v133, v133
	v_exp_f32_e32 v134, v134
	v_exp_f32_e32 v135, v135
	v_add_f32_e32 v246, v128, v129
	v_add_f32_e32 v246, v130, v246
	v_add_f32_e32 v246, v131, v246
	s_waitcnt lgkmcnt(2)
	v_mfma_f32_32x32x16_bf16 v[144:159], v[234:237], v[180:183], v[144:159]
	v_mfma_f32_32x32x16_bf16 v[144:159], v[238:241], v[176:179], v[144:159]
	ds_read_b128 v[234:237], v204 offset:0
	ds_read_b128 v[238:241], v205 offset:0
	v_exp_f32_e32 v136, v136
	v_exp_f32_e32 v137, v137
	v_exp_f32_e32 v138, v138
	v_exp_f32_e32 v139, v139
	v_add_f32_e32 v246, v132, v246
	v_add_f32_e32 v246, v133, v246
	v_add_f32_e32 v246, v134, v246
	v_add_f32_e32 v246, v135, v246
	s_waitcnt lgkmcnt(2)
	v_mfma_f32_32x32x16_bf16 v[144:159], v[226:229], v[172:175], v[144:159]
	v_mfma_f32_32x32x16_bf16 v[144:159], v[230:233], v[168:171], v[144:159]
	v_exp_f32_e32 v140, v140
	v_exp_f32_e32 v141, v141
	v_exp_f32_e32 v142, v142
	v_exp_f32_e32 v143, v143
	v_add_f32_e32 v246, v136, v246
	v_add_f32_e32 v246, v137, v246
	v_add_f32_e32 v246, v138, v246
	v_add_f32_e32 v246, v139, v246
	v_cvt_pk_bf16_f32 v226, v128, v129
	v_cvt_pk_bf16_f32 v227, v130, v131
	v_cvt_pk_bf16_f32 v228, v132, v133
	v_cvt_pk_bf16_f32 v229, v134, v135
	s_waitcnt lgkmcnt(0)
	v_mfma_f32_32x32x16_bf16 v[144:159], v[234:237], v[164:167], v[144:159]
	v_mfma_f32_32x32x16_bf16 v[144:159], v[238:241], v[160:163], v[144:159]
	s_waitcnt vmcnt(0)
	s_barrier
	s_add_u32 s86, s86, 0x4000
	s_addc_u32 s87, s87, 0
	s_add_u32 s2, s2, 0x8000
	s_addc_u32 s3, s3, 0
	v_add_u32_e32 v245, s84, v214
	s_sub_u32 s85, s84, 0x8000
	s_cmp_eq_u32 s84, 0
	s_cselect_b32 s85, 0x10000, s85
	ds_read_b64_tr_b16 v[234:235], v245 offset:0
	ds_read_b64_tr_b16 v[236:237], v245 offset:2048
	ds_read_b64_tr_b16 v[238:239], v245 offset:512
	ds_read_b64_tr_b16 v[240:241], v245 offset:2560
	ds_read_b64_tr_b16 v[128:129], v245 offset:4096
	ds_read_b64_tr_b16 v[130:131], v245 offset:6144
	ds_read_b64_tr_b16 v[132:133], v245 offset:4608
	ds_read_b64_tr_b16 v[134:135], v245 offset:6656
	v_add_f32_e32 v246, v140, v246
	v_add_f32_e32 v246, v141, v246
	v_add_f32_e32 v246, v142, v246
	v_add_f32_e32 v246, v143, v246
	v_cvt_pk_bf16_f32 v230, v136, v137
	v_cvt_pk_bf16_f32 v231, v138, v139
	v_cvt_pk_bf16_f32 v232, v140, v141
	v_cvt_pk_bf16_f32 v233, v142, v143
	v_add_f32_e32 v215, v215, v246
	ds_read_b64_tr_b16 v[136:137], v245 offset:1024
	ds_read_b64_tr_b16 v[138:139], v245 offset:3072
	ds_read_b64_tr_b16 v[140:141], v245 offset:1536
	ds_read_b64_tr_b16 v[142:143], v245 offset:3584
	s_waitcnt lgkmcnt(8)
	v_mfma_f32_32x32x16_bf16 v[112:127], v[226:229], v[234:237], v[112:127]
	v_mfma_f32_32x32x16_bf16 v[96:111], v[226:229], v[238:241], v[96:111]
	ds_read_b64_tr_b16 v[234:235], v245 offset:5120
	ds_read_b64_tr_b16 v[236:237], v245 offset:7168
	ds_read_b64_tr_b16 v[238:239], v245 offset:5632
	ds_read_b64_tr_b16 v[240:241], v245 offset:7680
	s_add_i32 s41, s85, s24
	s_add_i32 m0, s41, 0x8000
	s_nop 0
	global_load_lds_dwordx4 v218, s[2:3] sc1
	s_waitcnt lgkmcnt(8)
	v_mfma_f32_32x32x16_bf16 v[112:127], v[230:233], v[128:131], v[112:127]
	v_mfma_f32_32x32x16_bf16 v[96:111], v[230:233], v[132:135], v[96:111]
	ds_read_b64_tr_b16 v[128:129], v245 offset:16384
	ds_read_b64_tr_b16 v[130:131], v245 offset:18432
	ds_read_b64_tr_b16 v[132:133], v245 offset:16896
	ds_read_b64_tr_b16 v[134:135], v245 offset:18944
	s_add_i32 s41, s85, s24
	s_add_i32 m0, s41, 0xa000
	s_nop 0
	global_load_lds_dwordx4 v217, s[2:3] sc1
	s_waitcnt lgkmcnt(8)
	v_mfma_f32_32x32x16_bf16 v[80:95], v[226:229], v[136:139], v[80:95]
	v_mfma_f32_32x32x16_bf16 v[64:79], v[226:229], v[140:143], v[64:79]
	ds_read_b64_tr_b16 v[136:137], v245 offset:20480
	ds_read_b64_tr_b16 v[138:139], v245 offset:22528
	ds_read_b64_tr_b16 v[140:141], v245 offset:20992
	ds_read_b64_tr_b16 v[142:143], v245 offset:23040
	s_add_i32 s41, s85, s24
	s_add_i32 m0, s41, 0xc000
	s_nop 0
	global_load_lds_dwordx4 v242, s[2:3] sc1
	s_waitcnt lgkmcnt(8)
	v_mfma_f32_32x32x16_bf16 v[80:95], v[230:233], v[234:237], v[80:95]
	v_mfma_f32_32x32x16_bf16 v[64:79], v[230:233], v[238:241], v[64:79]
	ds_read_b64_tr_b16 v[234:235], v245 offset:17408
	ds_read_b64_tr_b16 v[236:237], v245 offset:19456
	ds_read_b64_tr_b16 v[238:239], v245 offset:17920
	ds_read_b64_tr_b16 v[240:241], v245 offset:19968
	s_add_i32 s41, s85, s24
	s_add_i32 m0, s41, 0xe000
	s_nop 0
	global_load_lds_dwordx4 v243, s[2:3] sc1
	s_waitcnt lgkmcnt(8)
	v_mfma_f32_32x32x16_bf16 v[48:63], v[226:229], v[128:131], v[48:63]
	v_mfma_f32_32x32x16_bf16 v[32:47], v[226:229], v[132:135], v[32:47]
	ds_read_b64_tr_b16 v[128:129], v245 offset:21504
	ds_read_b64_tr_b16 v[130:131], v245 offset:23552
	ds_read_b64_tr_b16 v[132:133], v245 offset:22016
	ds_read_b64_tr_b16 v[134:135], v245 offset:24064
	s_mov_b32 m0, s24
	s_nop 0
	global_load_lds_dwordx4 v220, s[86:87] sc1
	s_waitcnt lgkmcnt(8)
	v_mfma_f32_32x32x16_bf16 v[48:63], v[230:233], v[136:139], v[48:63]
	v_mfma_f32_32x32x16_bf16 v[32:47], v[230:233], v[140:143], v[32:47]
	s_add_i32 m0, s24, 0x2000
	s_nop 0
	global_load_lds_dwordx4 v219, s[86:87] sc1
	s_waitcnt lgkmcnt(0)
	v_mfma_f32_32x32x16_bf16 v[16:31], v[226:229], v[234:237], v[16:31]
	v_mfma_f32_32x32x16_bf16 v[0:15], v[226:229], v[238:241], v[0:15]
	v_mfma_f32_32x32x16_bf16 v[16:31], v[230:233], v[128:131], v[16:31]
	s_add_i32 s84, s84, 0x8000
	s_cmp_eq_u32 s84, 0x18000
	s_cselect_b32 s84, 0, s84
	s_add_i32 s25, s25, 1
	s_cmpk_eq_i32 s25, 0x82
	v_mfma_f32_32x32x16_bf16 v[0:15], v[230:233], v[132:135], v[0:15]
	s_cbranch_scc0 .LattnB_m0
	s_waitcnt vmcnt(0)
	s_barrier

; #define SBAR() __builtin_amdgcn_sched_barrier(0)
; #define PVR(S, DA, DB, vbase) do { S[0] = tr_read<v_rd_off(DA, 0, 0)>(vbase); S[1] = tr_read<v_rd_off(DA, 0, 1)>(vbase); S[2] = tr_read<v_rd_off(DB, 0, 0)>(vbase); S[3] = tr_read<v_rd_off(DB, 0, 1)>(vbase); \
;     S[4] = tr_read<v_rd_off(DA, 1, 0)>(vbase); S[5] = tr_read<v_rd_off(DA, 1, 1)>(vbase); S[6] = tr_read<v_rd_off(DB, 1, 0)>(vbase); S[7] = tr_read<v_rd_off(DB, 1, 1)>(vbase); } while (0)
; #define RAWBAR() do { asm volatile("s_waitcnt lgkmcnt(0)" ::: "memory"); __builtin_amdgcn_s_barrier(); asm volatile("" ::: "memory"); } while (0)
; #define RAWBAR() do { asm volatile("s_waitcnt lgkmcnt(0)" ::: "memory"); __builtin_amdgcn_s_barrier(); asm volatile("" ::: "memory"); } while (0)
; #define RAWBAR() do { asm volatile("s_waitcnt lgkmcnt(0)" ::: "memory"); __builtin_amdgcn_s_barrier(); asm volatile("" ::: "memory"); } while (0)
; #define RAWBAR() do { asm volatile("s_waitcnt lgkmcnt(0)" ::: "memory"); __builtin_amdgcn_s_barrier(); asm volatile("" ::: "memory"); } while (0)
; #define RAWBAR() do { asm volatile("s_waitcnt lgkmcnt(0)" ::: "memory"); __builtin_amdgcn_s_barrier(); asm volatile("" ::: "memory"); } while (0)
; template <int MODE> ...
;     ...
;   for (int j = 0; j < NT; ++j) {
;     const int buf = j & 1;
;     if (j + 1 < NT) { STAGE((j + 1) * KVBLK, buf ^ 1); }
;     const char* Kb = K_lds + buf * 16384;
;     f32x16 pe = {}, po = {};
; #pragma unroll
;     for (int d0 = 0; d0 < 8; d0 += 2) {
;       const bf16x8 k0 = *reinterpret_cast<const bf16x8*>(Kb + KSWZ(krow, (d0 * 16 + hi * 8) * 2));
;       const bf16x8 k1 = *reinterpret_cast<const bf16x8*>(Kb + KSWZ(krow, ((d0 + 1) * 16 + hi * 8) * 2));
;       pe = __builtin_amdgcn_mfma_f32_32x32x16_bf16(k0, qr[d0], pe, 0, 0, 0);
;       po = __builtin_amdgcn_mfma_f32_32x32x16_bf16(k1, qr[d0 + 1], po, 0, 0, 0); }
;     const int vo = vb0 + buf * 32768;
;     s16x4 R0_[8], R1_[8];
;     PVR(R0_, 0, 1, vo);
;     f32x16 p;
; #pragma unroll
;     for (int r = 0; r < 16; ++r) p[r] = __builtin_amdgcn_exp2f(fmaf(pe[r] + po[r], C, negMc));
;     float ps = 0.f;
; #pragma unroll
;     for (int r = 0; r < 16; ++r) ps += p[r];
;     lsum += ps;
;     const bf16x8 own0 = pk8(p, 0), own1 = pk8(p, 8);
;     SBAR();
;     PV_TAIL4(o, vo, vo + 16384, own0, own1);
;     asm volatile("s_waitcnt vmcnt(0)" ::: "memory");
;     RAWBAR();
;   }
.LBB0_1023:
	ds_read_b128 v[230:233], v229 offset:16384
	ds_read_b128 v[234:237], v228 offset:16384
	ds_read_b128 v[238:241], v227 offset:16384
	ds_read_b128 v[242:245], v226 offset:16384
	v_exp_f32_e32 v144, v144
	v_exp_f32_e32 v145, v145
	v_exp_f32_e32 v146, v146
	v_exp_f32_e32 v147, v147
	s_waitcnt lgkmcnt(2)
	v_mfma_f32_32x32x16_bf16 v[128:143], v[230:233], v[188:191], 0
	v_mfma_f32_32x32x16_bf16 v[128:143], v[234:237], v[184:187], v[128:143]
	ds_read_b128 v[230:233], v204 offset:16384
	ds_read_b128 v[234:237], v205 offset:16384
	s_mov_b32 m0, s34
	s_nop 0
	global_load_lds_dwordx4 v225, s[86:87] sc1
	v_exp_f32_e32 v148, v148
	v_exp_f32_e32 v149, v149
	v_exp_f32_e32 v150, v150
	v_exp_f32_e32 v151, v151
	v_add_f32_e32 v250, v144, v145
	v_add_f32_e32 v250, v146, v250
	v_add_f32_e32 v250, v147, v250
	s_waitcnt lgkmcnt(2)
	v_mfma_f32_32x32x16_bf16 v[128:143], v[238:241], v[180:183], v[128:143]
	v_mfma_f32_32x32x16_bf16 v[128:143], v[242:245], v[176:179], v[128:143]
	ds_read_b128 v[238:241], v206 offset:16384
	ds_read_b128 v[242:245], v207 offset:16384
	s_add_i32 m0, s34, 0x2000
	s_nop 0
	global_load_lds_dwordx4 v223, s[86:87] sc1
	v_exp_f32_e32 v152, v152
	v_exp_f32_e32 v153, v153
	v_exp_f32_e32 v154, v154
	v_exp_f32_e32 v155, v155
	v_add_f32_e32 v250, v148, v250
	v_add_f32_e32 v250, v149, v250
	v_add_f32_e32 v250, v150, v250
	v_add_f32_e32 v250, v151, v250
	s_waitcnt lgkmcnt(2)
	v_mfma_f32_32x32x16_bf16 v[128:143], v[230:233], v[172:175], v[128:143]
	v_mfma_f32_32x32x16_bf16 v[128:143], v[234:237], v[168:171], v[128:143]
	v_exp_f32_e32 v156, v156
	v_exp_f32_e32 v157, v157
	v_exp_f32_e32 v158, v158
	v_exp_f32_e32 v159, v159
	v_add_f32_e32 v250, v152, v250
	v_add_f32_e32 v250, v153, v250
	v_add_f32_e32 v250, v154, v250
	v_add_f32_e32 v250, v155, v250
	v_cvt_pk_bf16_f32 v230, v144, v145
	v_cvt_pk_bf16_f32 v231, v146, v147
	v_cvt_pk_bf16_f32 v232, v148, v149
	v_cvt_pk_bf16_f32 v233, v150, v151
	s_waitcnt lgkmcnt(0)
	v_mfma_f32_32x32x16_bf16 v[128:143], v[238:241], v[164:167], v[128:143]
	v_mfma_f32_32x32x16_bf16 v[128:143], v[242:245], v[160:163], v[128:143]
	v_add_u32_e32 v249, s84, v218
	s_add_i32 s85, s84, 0x8000
	s_cmp_eq_u32 s85, 0x18000
	s_cselect_b32 s85, 0, s85
	ds_read_b64_tr_b16 v[238:239], v249 offset:0
	ds_read_b64_tr_b16 v[240:241], v249 offset:2048
	ds_read_b64_tr_b16 v[242:243], v249 offset:512
	ds_read_b64_tr_b16 v[244:245], v249 offset:2560
	ds_read_b64_tr_b16 v[144:145], v249 offset:4096
	ds_read_b64_tr_b16 v[146:147], v249 offset:6144
	ds_read_b64_tr_b16 v[148:149], v249 offset:4608
	ds_read_b64_tr_b16 v[150:151], v249 offset:6656
	v_add_f32_e32 v250, v156, v250
	v_add_f32_e32 v250, v157, v250
	v_add_f32_e32 v250, v158, v250
	v_add_f32_e32 v250, v159, v250
	v_cvt_pk_bf16_f32 v234, v152, v153
	v_cvt_pk_bf16_f32 v235, v154, v155
	v_cvt_pk_bf16_f32 v236, v156, v157
	v_cvt_pk_bf16_f32 v237, v158, v159
	v_add_f32_e32 v219, v219, v250
	ds_read_b64_tr_b16 v[152:153], v249 offset:1024
	ds_read_b64_tr_b16 v[154:155], v249 offset:3072
	ds_read_b64_tr_b16 v[156:157], v249 offset:1536
	ds_read_b64_tr_b16 v[158:159], v249 offset:3584
	s_waitcnt lgkmcnt(8)
	v_mfma_f32_32x32x16_bf16 v[112:127], v[230:233], v[238:241], v[112:127]
	v_mfma_f32_32x32x16_bf16 v[96:111], v[230:233], v[242:245], v[96:111]
	ds_read_b64_tr_b16 v[238:239], v249 offset:5120
	ds_read_b64_tr_b16 v[240:241], v249 offset:7168
	ds_read_b64_tr_b16 v[242:243], v249 offset:5632
	ds_read_b64_tr_b16 v[244:245], v249 offset:7680
	s_add_i32 s30, s85, s34
	s_add_i32 m0, s30, 0x8000
	s_nop 0
	global_load_lds_dwordx4 v222, s[2:3] sc1
	s_waitcnt lgkmcnt(8)
	v_mfma_f32_32x32x16_bf16 v[112:127], v[234:237], v[144:147], v[112:127]
	v_mfma_f32_32x32x16_bf16 v[96:111], v[234:237], v[148:151], v[96:111]
	ds_read_b64_tr_b16 v[144:145], v249 offset:16384
	ds_read_b64_tr_b16 v[146:147], v249 offset:18432
	ds_read_b64_tr_b16 v[148:149], v249 offset:16896
	ds_read_b64_tr_b16 v[150:151], v249 offset:18944
	s_add_i32 s30, s85, s34
	s_add_i32 m0, s30, 0xa000
	s_nop 0
	global_load_lds_dwordx4 v221, s[2:3] sc1
	s_waitcnt lgkmcnt(8)
	v_mfma_f32_32x32x16_bf16 v[80:95], v[230:233], v[152:155], v[80:95]
	v_mfma_f32_32x32x16_bf16 v[64:79], v[230:233], v[156:159], v[64:79]
	ds_read_b64_tr_b16 v[152:153], v249 offset:20480
	ds_read_b64_tr_b16 v[154:155], v249 offset:22528
	ds_read_b64_tr_b16 v[156:157], v249 offset:20992
	ds_read_b64_tr_b16 v[158:159], v249 offset:23040
	s_add_i32 s30, s85, s34
	s_add_i32 m0, s30, 0xc000
	s_nop 0
	global_load_lds_dwordx4 v246, s[2:3] sc1
	s_waitcnt lgkmcnt(8)
	v_mfma_f32_32x32x16_bf16 v[80:95], v[234:237], v[238:241], v[80:95]
	v_mfma_f32_32x32x16_bf16 v[64:79], v[234:237], v[242:245], v[64:79]
	ds_read_b64_tr_b16 v[238:239], v249 offset:17408
	ds_read_b64_tr_b16 v[240:241], v249 offset:19456
	ds_read_b64_tr_b16 v[242:243], v249 offset:17920
	ds_read_b64_tr_b16 v[244:245], v249 offset:19968
	s_add_i32 s30, s85, s34
	s_add_i32 m0, s30, 0xe000
	s_nop 0
	global_load_lds_dwordx4 v247, s[2:3] sc1
	s_waitcnt lgkmcnt(8)
	v_mfma_f32_32x32x16_bf16 v[32:47], v[230:233], v[144:147], v[32:47]
	v_mfma_f32_32x32x16_bf16 v[16:31], v[230:233], v[148:151], v[16:31]
	ds_read_b64_tr_b16 v[144:145], v249 offset:21504
	ds_read_b64_tr_b16 v[146:147], v249 offset:23552
	ds_read_b64_tr_b16 v[148:149], v249 offset:22016
	ds_read_b64_tr_b16 v[150:151], v249 offset:24064
	s_waitcnt lgkmcnt(8)
	v_mfma_f32_32x32x16_bf16 v[32:47], v[234:237], v[152:155], v[32:47]
	v_mfma_f32_32x32x16_bf16 v[16:31], v[234:237], v[156:159], v[16:31]
	s_waitcnt lgkmcnt(0)
	v_mfma_f32_32x32x16_bf16 v[48:63], v[230:233], v[238:241], v[48:63]
	s_waitcnt vmcnt(0)
	s_barrier
; #define SBAR() __builtin_amdgcn_sched_barrier(0)
; #define PVR(S, DA, DB, vbase) do { S[0] = tr_read<v_rd_off(DA, 0, 0)>(vbase); S[1] = tr_read<v_rd_off(DA, 0, 1)>(vbase); S[2] = tr_read<v_rd_off(DB, 0, 0)>(vbase); S[3] = tr_read<v_rd_off(DB, 0, 1)>(vbase); \
;     S[4] = tr_read<v_rd_off(DA, 1, 0)>(vbase); S[5] = tr_read<v_rd_off(DA, 1, 1)>(vbase); S[6] = tr_read<v_rd_off(DB, 1, 0)>(vbase); S[7] = tr_read<v_rd_off(DB, 1, 1)>(vbase); } while (0)
; #define RAWBAR() do { asm volatile("s_waitcnt lgkmcnt(0)" ::: "memory"); __builtin_amdgcn_s_barrier(); asm volatile("" ::: "memory"); } while (0)
; #define RAWBAR() do { asm volatile("s_waitcnt lgkmcnt(0)" ::: "memory"); __builtin_amdgcn_s_barrier(); asm volatile("" ::: "memory"); } while (0)
; #define RAWBAR() do { asm volatile("s_waitcnt lgkmcnt(0)" ::: "memory"); __builtin_amdgcn_s_barrier(); asm volatile("" ::: "memory"); } while (0)
; #define RAWBAR() do { asm volatile("s_waitcnt lgkmcnt(0)" ::: "memory"); __builtin_amdgcn_s_barrier(); asm volatile("" ::: "memory"); } while (0)
; #define RAWBAR() do { asm volatile("s_waitcnt lgkmcnt(0)" ::: "memory"); __builtin_amdgcn_s_barrier(); asm volatile("" ::: "memory"); } while (0)
; template <int MODE> ...
;     ...
;   for (int j = 0; j < NT; ++j) {
;     const int buf = j & 1;
;     if (j + 1 < NT) { STAGE((j + 1) * KVBLK, buf ^ 1); }
;     const char* Kb = K_lds + buf * 16384;
;     f32x16 pe = {}, po = {};
; #pragma unroll
;     for (int d0 = 0; d0 < 8; d0 += 2) {
;       const bf16x8 k0 = *reinterpret_cast<const bf16x8*>(Kb + KSWZ(krow, (d0 * 16 + hi * 8) * 2));
;       const bf16x8 k1 = *reinterpret_cast<const bf16x8*>(Kb + KSWZ(krow, ((d0 + 1) * 16 + hi * 8) * 2));
;       pe = __builtin_amdgcn_mfma_f32_32x32x16_bf16(k0, qr[d0], pe, 0, 0, 0);
;       po = __builtin_amdgcn_mfma_f32_32x32x16_bf16(k1, qr[d0 + 1], po, 0, 0, 0); }
;     const int vo = vb0 + buf * 32768;
;     s16x4 R0_[8], R1_[8];
;     PVR(R0_, 0, 1, vo);
;     f32x16 p;
; #pragma unroll
;     for (int r = 0; r < 16; ++r) p[r] = __builtin_amdgcn_exp2f(fmaf(pe[r] + po[r], C, negMc));
;     float ps = 0.f;
; #pragma unroll
;     for (int r = 0; r < 16; ++r) ps += p[r];
;     lsum += ps;
;     const bf16x8 own0 = pk8(p, 0), own1 = pk8(p, 8);
;     SBAR();
;     PV_TAIL4(o, vo, vo + 16384, own0, own1);
;     asm volatile("s_waitcnt vmcnt(0)" ::: "memory");
;     RAWBAR();
;   }
	s_add_u32 s86, s86, 0x4000
	s_addc_u32 s87, s87, 0
	s_add_u32 s2, s2, 0x8000
	s_addc_u32 s3, s3, 0
	v_mfma_f32_32x32x16_bf16 v[0:15], v[230:233], v[242:245], v[0:15]
	v_mfma_f32_32x32x16_bf16 v[48:63], v[234:237], v[144:147], v[48:63]
	s_add_i32 s84, s84, 0x8000
	s_cmp_eq_u32 s84, 0x18000
	s_cselect_b32 s84, 0, s84
	v_mfma_f32_32x32x16_bf16 v[0:15], v[234:237], v[148:151], v[0:15]
	ds_read_b128 v[230:233], v229 offset:0
	ds_read_b128 v[234:237], v228 offset:0
	ds_read_b128 v[238:241], v227 offset:0
	ds_read_b128 v[242:245], v226 offset:0
	v_exp_f32_e32 v128, v128
	v_exp_f32_e32 v129, v129
	v_exp_f32_e32 v130, v130
	v_exp_f32_e32 v131, v131
	s_waitcnt lgkmcnt(2)
	v_mfma_f32_32x32x16_bf16 v[144:159], v[230:233], v[188:191], 0
	v_mfma_f32_32x32x16_bf16 v[144:159], v[234:237], v[184:187], v[144:159]
	ds_read_b128 v[230:233], v204 offset:0
	ds_read_b128 v[234:237], v205 offset:0
	s_add_i32 m0, s34, 0x4000
	s_nop 0
	global_load_lds_dwordx4 v225, s[86:87] sc1
	v_exp_f32_e32 v132, v132
	v_exp_f32_e32 v133, v133
	v_exp_f32_e32 v134, v134
	v_exp_f32_e32 v135, v135
	v_add_f32_e32 v250, v128, v129
	v_add_f32_e32 v250, v130, v250
	v_add_f32_e32 v250, v131, v250
	s_waitcnt lgkmcnt(2)
	v_mfma_f32_32x32x16_bf16 v[144:159], v[238:241], v[180:183], v[144:159]
	v_mfma_f32_32x32x16_bf16 v[144:159], v[242:245], v[176:179], v[144:159]
	ds_read_b128 v[238:241], v206 offset:0
	ds_read_b128 v[242:245], v207 offset:0
	s_add_i32 m0, s34, 0x6000
	s_nop 0
	global_load_lds_dwordx4 v223, s[86:87] sc1
	v_exp_f32_e32 v136, v136
	v_exp_f32_e32 v137, v137
	v_exp_f32_e32 v138, v138
	v_exp_f32_e32 v139, v139
	v_add_f32_e32 v250, v132, v250
	v_add_f32_e32 v250, v133, v250
	v_add_f32_e32 v250, v134, v250
	v_add_f32_e32 v250, v135, v250
	s_waitcnt lgkmcnt(2)
	v_mfma_f32_32x32x16_bf16 v[144:159], v[230:233], v[172:175], v[144:159]
	v_mfma_f32_32x32x16_bf16 v[144:159], v[234:237], v[168:171], v[144:159]
	v_exp_f32_e32 v140, v140
	v_exp_f32_e32 v141, v141
	v_exp_f32_e32 v142, v142
	v_exp_f32_e32 v143, v143
	v_add_f32_e32 v250, v136, v250
	v_add_f32_e32 v250, v137, v250
	v_add_f32_e32 v250, v138, v250
	v_add_f32_e32 v250, v139, v250
	v_cvt_pk_bf16_f32 v230, v128, v129
	v_cvt_pk_bf16_f32 v231, v130, v131
	v_cvt_pk_bf16_f32 v232, v132, v133
	v_cvt_pk_bf16_f32 v233, v134, v135
	s_waitcnt lgkmcnt(0)
	v_mfma_f32_32x32x16_bf16 v[144:159], v[238:241], v[164:167], v[144:159]
	v_mfma_f32_32x32x16_bf16 v[144:159], v[242:245], v[160:163], v[144:159]
	v_add_u32_e32 v249, s84, v218
	s_add_i32 s85, s84, 0x8000
	s_cmp_eq_u32 s85, 0x18000
	s_cselect_b32 s85, 0, s85
	ds_read_b64_tr_b16 v[238:239], v249 offset:0
	ds_read_b64_tr_b16 v[240:241], v249 offset:2048
	ds_read_b64_tr_b16 v[242:243], v249 offset:512
	ds_read_b64_tr_b16 v[244:245], v249 offset:2560
	ds_read_b64_tr_b16 v[128:129], v249 offset:4096
	ds_read_b64_tr_b16 v[130:131], v249 offset:6144
	ds_read_b64_tr_b16 v[132:133], v249 offset:4608
	ds_read_b64_tr_b16 v[134:135], v249 offset:6656
	v_add_f32_e32 v250, v140, v250
	v_add_f32_e32 v250, v141, v250
	v_add_f32_e32 v250, v142, v250
	v_add_f32_e32 v250, v143, v250
	v_cvt_pk_bf16_f32 v234, v136, v137
	v_cvt_pk_bf16_f32 v235, v138, v139
	v_cvt_pk_bf16_f32 v236, v140, v141
	v_cvt_pk_bf16_f32 v237, v142, v143
	v_add_f32_e32 v219, v219, v250
	ds_read_b64_tr_b16 v[136:137], v249 offset:1024
	ds_read_b64_tr_b16 v[138:139], v249 offset:3072
	ds_read_b64_tr_b16 v[140:141], v249 offset:1536
	ds_read_b64_tr_b16 v[142:143], v249 offset:3584
	s_waitcnt lgkmcnt(8)
	v_mfma_f32_32x32x16_bf16 v[112:127], v[230:233], v[238:241], v[112:127]
	v_mfma_f32_32x32x16_bf16 v[96:111], v[230:233], v[242:245], v[96:111]
	ds_read_b64_tr_b16 v[238:239], v249 offset:5120
	ds_read_b64_tr_b16 v[240:241], v249 offset:7168
	ds_read_b64_tr_b16 v[242:243], v249 offset:5632
	ds_read_b64_tr_b16 v[244:245], v249 offset:7680
	s_add_i32 s30, s85, s34
	s_add_i32 m0, s30, 0x8000
	s_nop 0
	global_load_lds_dwordx4 v222, s[2:3] sc1
	s_waitcnt lgkmcnt(8)
	v_mfma_f32_32x32x16_bf16 v[112:127], v[234:237], v[128:131], v[112:127]
	v_mfma_f32_32x32x16_bf16 v[96:111], v[234:237], v[132:135], v[96:111]
	ds_read_b64_tr_b16 v[128:129], v249 offset:16384
	ds_read_b64_tr_b16 v[130:131], v249 offset:18432
	ds_read_b64_tr_b16 v[132:133], v249 offset:16896
	ds_read_b64_tr_b16 v[134:135], v249 offset:18944
	s_add_i32 s30, s85, s34
	s_add_i32 m0, s30, 0xa000
	s_nop 0
	global_load_lds_dwordx4 v221, s[2:3] sc1
	s_waitcnt lgkmcnt(8)
	v_mfma_f32_32x32x16_bf16 v[80:95], v[230:233], v[136:139], v[80:95]
	v_mfma_f32_32x32x16_bf16 v[64:79], v[230:233], v[140:143], v[64:79]
	ds_read_b64_tr_b16 v[136:137], v249 offset:20480
	ds_read_b64_tr_b16 v[138:139], v249 offset:22528
	ds_read_b64_tr_b16 v[140:141], v249 offset:20992
	ds_read_b64_tr_b16 v[142:143], v249 offset:23040
	s_add_i32 s30, s85, s34
	s_add_i32 m0, s30, 0xc000
	s_nop 0
	global_load_lds_dwordx4 v246, s[2:3] sc1
	s_waitcnt lgkmcnt(8)
	v_mfma_f32_32x32x16_bf16 v[80:95], v[234:237], v[238:241], v[80:95]
	v_mfma_f32_32x32x16_bf16 v[64:79], v[234:237], v[242:245], v[64:79]
	ds_read_b64_tr_b16 v[238:239], v249 offset:17408
	ds_read_b64_tr_b16 v[240:241], v249 offset:19456
	ds_read_b64_tr_b16 v[242:243], v249 offset:17920
	ds_read_b64_tr_b16 v[244:245], v249 offset:19968
	s_add_i32 s30, s85, s34
	s_add_i32 m0, s30, 0xe000
	s_nop 0
	global_load_lds_dwordx4 v247, s[2:3] sc1
	s_waitcnt lgkmcnt(8)
	v_mfma_f32_32x32x16_bf16 v[32:47], v[230:233], v[128:131], v[32:47]
	v_mfma_f32_32x32x16_bf16 v[16:31], v[230:233], v[132:135], v[16:31]
	ds_read_b64_tr_b16 v[128:129], v249 offset:21504
	ds_read_b64_tr_b16 v[130:131], v249 offset:23552
	ds_read_b64_tr_b16 v[132:133], v249 offset:22016
	ds_read_b64_tr_b16 v[134:135], v249 offset:24064
	s_waitcnt lgkmcnt(8)
	v_mfma_f32_32x32x16_bf16 v[32:47], v[234:237], v[136:139], v[32:47]
	v_mfma_f32_32x32x16_bf16 v[16:31], v[234:237], v[140:143], v[16:31]
	s_waitcnt lgkmcnt(0)
	v_mfma_f32_32x32x16_bf16 v[48:63], v[230:233], v[238:241], v[48:63]
	s_waitcnt vmcnt(0)
	s_barrier
	s_add_u32 s86, s86, 0x4000
	s_addc_u32 s87, s87, 0
	s_add_u32 s2, s2, 0x8000
	s_addc_u32 s3, s3, 0
	v_mfma_f32_32x32x16_bf16 v[0:15], v[230:233], v[242:245], v[0:15]
	v_mfma_f32_32x32x16_bf16 v[48:63], v[234:237], v[128:131], v[48:63]
	s_add_i32 s84, s84, 0x8000
	s_cmp_eq_u32 s84, 0x18000
	s_cselect_b32 s84, 0, s84
	s_add_i32 s40, s40, 1
	s_cmpk_eq_i32 s40, 0x82
	v_mfma_f32_32x32x16_bf16 v[0:15], v[234:237], v[132:135], v[0:15]
	s_cbranch_scc0 .LBB0_1023
	s_barrier
	s_branch .Lattn_join_m1

; #define SBAR() __builtin_amdgcn_sched_barrier(0)
; #define PVR(S, DA, DB, vbase) do { S[0] = tr_read<v_rd_off(DA, 0, 0)>(vbase); S[1] = tr_read<v_rd_off(DA, 0, 1)>(vbase); S[2] = tr_read<v_rd_off(DB, 0, 0)>(vbase); S[3] = tr_read<v_rd_off(DB, 0, 1)>(vbase); \
;     S[4] = tr_read<v_rd_off(DA, 1, 0)>(vbase); S[5] = tr_read<v_rd_off(DA, 1, 1)>(vbase); S[6] = tr_read<v_rd_off(DB, 1, 0)>(vbase); S[7] = tr_read<v_rd_off(DB, 1, 1)>(vbase); } while (0)
; #define RAWBAR() do { asm volatile("s_waitcnt lgkmcnt(0)" ::: "memory"); __builtin_amdgcn_s_barrier(); asm volatile("" ::: "memory"); } while (0)
; #define RAWBAR() do { asm volatile("s_waitcnt lgkmcnt(0)" ::: "memory"); __builtin_amdgcn_s_barrier(); asm volatile("" ::: "memory"); } while (0)
; #define RAWBAR() do { asm volatile("s_waitcnt lgkmcnt(0)" ::: "memory"); __builtin_amdgcn_s_barrier(); asm volatile("" ::: "memory"); } while (0)
; #define RAWBAR() do { asm volatile("s_waitcnt lgkmcnt(0)" ::: "memory"); __builtin_amdgcn_s_barrier(); asm volatile("" ::: "memory"); } while (0)
; #define RAWBAR() do { asm volatile("s_waitcnt lgkmcnt(0)" ::: "memory"); __builtin_amdgcn_s_barrier(); asm volatile("" ::: "memory"); } while (0)
; template <int MODE> ...
;     ...
;   for (int j = 0; j < NT; ++j) {
;     const int buf = j & 1;
;     if (j + 1 < NT) { STAGE((j + 1) * KVBLK, buf ^ 1); }
;     const char* Kb = K_lds + buf * 16384;
;     f32x16 pe = {}, po = {};
; #pragma unroll
;     for (int d0 = 0; d0 < 8; d0 += 2) {
;       const bf16x8 k0 = *reinterpret_cast<const bf16x8*>(Kb + KSWZ(krow, (d0 * 16 + hi * 8) * 2));
;       const bf16x8 k1 = *reinterpret_cast<const bf16x8*>(Kb + KSWZ(krow, ((d0 + 1) * 16 + hi * 8) * 2));
;       pe = __builtin_amdgcn_mfma_f32_32x32x16_bf16(k0, qr[d0], pe, 0, 0, 0);
;       po = __builtin_amdgcn_mfma_f32_32x32x16_bf16(k1, qr[d0 + 1], po, 0, 0, 0); }
;     const int vo = vb0 + buf * 32768;
;     s16x4 R0_[8], R1_[8];
;     PVR(R0_, 0, 1, vo);
;     f32x16 p;
; #pragma unroll
;     for (int r = 0; r < 16; ++r) p[r] = __builtin_amdgcn_exp2f(fmaf(pe[r] + po[r], C, negMc));
;     float ps = 0.f;
; #pragma unroll
;     for (int r = 0; r < 16; ++r) ps += p[r];
;     lsum += ps;
;     const bf16x8 own0 = pk8(p, 0), own1 = pk8(p, 8);
;     SBAR();
;     PV_TAIL4(o, vo, vo + 16384, own0, own1);
;     asm volatile("s_waitcnt vmcnt(0)" ::: "memory");
;     RAWBAR();
;   }
.LattnB_m1:
	ds_read_b128 v[230:233], v229 offset:16384
	ds_read_b128 v[234:237], v228 offset:16384
	ds_read_b128 v[238:241], v227 offset:16384
	ds_read_b128 v[242:245], v226 offset:16384
	v_exp_f32_e32 v144, v144
	v_exp_f32_e32 v145, v145
	v_exp_f32_e32 v146, v146
	v_exp_f32_e32 v147, v147
	s_waitcnt lgkmcnt(2)
	v_mfma_f32_32x32x16_bf16 v[128:143], v[230:233], v[188:191], 0
	v_mfma_f32_32x32x16_bf16 v[128:143], v[234:237], v[184:187], v[128:143]
	ds_read_b128 v[230:233], v204 offset:16384
	ds_read_b128 v[234:237], v205 offset:16384
	v_exp_f32_e32 v148, v148
	v_exp_f32_e32 v149, v149
	v_exp_f32_e32 v150, v150
	v_exp_f32_e32 v151, v151
	v_add_f32_e32 v250, v144, v145
	v_add_f32_e32 v250, v146, v250
	v_add_f32_e32 v250, v147, v250
	s_waitcnt lgkmcnt(2)
	v_mfma_f32_32x32x16_bf16 v[128:143], v[238:241], v[180:183], v[128:143]
	v_mfma_f32_32x32x16_bf16 v[128:143], v[242:245], v[176:179], v[128:143]
	ds_read_b128 v[238:241], v206 offset:16384
	ds_read_b128 v[242:245], v207 offset:16384
	v_exp_f32_e32 v152, v152
	v_exp_f32_e32 v153, v153
	v_exp_f32_e32 v154, v154
	v_exp_f32_e32 v155, v155
	v_add_f32_e32 v250, v148, v250
	v_add_f32_e32 v250, v149, v250
	v_add_f32_e32 v250, v150, v250
	v_add_f32_e32 v250, v151, v250
	s_waitcnt lgkmcnt(2)
	v_mfma_f32_32x32x16_bf16 v[128:143], v[230:233], v[172:175], v[128:143]
	v_mfma_f32_32x32x16_bf16 v[128:143], v[234:237], v[168:171], v[128:143]
	v_exp_f32_e32 v156, v156
	v_exp_f32_e32 v157, v157
	v_exp_f32_e32 v158, v158
	v_exp_f32_e32 v159, v159
	v_add_f32_e32 v250, v152, v250
	v_add_f32_e32 v250, v153, v250
	v_add_f32_e32 v250, v154, v250
	v_add_f32_e32 v250, v155, v250
	v_cvt_pk_bf16_f32 v230, v144, v145
	v_cvt_pk_bf16_f32 v231, v146, v147
	v_cvt_pk_bf16_f32 v232, v148, v149
	v_cvt_pk_bf16_f32 v233, v150, v151
	s_waitcnt lgkmcnt(0)
	v_mfma_f32_32x32x16_bf16 v[128:143], v[238:241], v[164:167], v[128:143]
	v_mfma_f32_32x32x16_bf16 v[128:143], v[242:245], v[160:163], v[128:143]
	s_waitcnt vmcnt(0)
	s_barrier
	s_add_u32 s86, s86, 0x4000
	s_addc_u32 s87, s87, 0
	s_add_u32 s2, s2, 0x8000
	s_addc_u32 s3, s3, 0
	v_add_u32_e32 v249, s84, v218
	s_sub_u32 s85, s84, 0x8000
	s_cmp_eq_u32 s84, 0
	s_cselect_b32 s85, 0x10000, s85
	ds_read_b64_tr_b16 v[238:239], v249 offset:0
	ds_read_b64_tr_b16 v[240:241], v249 offset:2048
	ds_read_b64_tr_b16 v[242:243], v249 offset:512
	ds_read_b64_tr_b16 v[244:245], v249 offset:2560
	ds_read_b64_tr_b16 v[144:145], v249 offset:4096
	ds_read_b64_tr_b16 v[146:147], v249 offset:6144
	ds_read_b64_tr_b16 v[148:149], v249 offset:4608
	ds_read_b64_tr_b16 v[150:151], v249 offset:6656
	v_add_f32_e32 v250, v156, v250
	v_add_f32_e32 v250, v157, v250
	v_add_f32_e32 v250, v158, v250
	v_add_f32_e32 v250, v159, v250
	v_cvt_pk_bf16_f32 v234, v152, v153
	v_cvt_pk_bf16_f32 v235, v154, v155
	v_cvt_pk_bf16_f32 v236, v156, v157
	v_cvt_pk_bf16_f32 v237, v158, v159
	v_add_f32_e32 v219, v219, v250
	ds_read_b64_tr_b16 v[152:153], v249 offset:1024
	ds_read_b64_tr_b16 v[154:155], v249 offset:3072
	ds_read_b64_tr_b16 v[156:157], v249 offset:1536
	ds_read_b64_tr_b16 v[158:159], v249 offset:3584
	s_waitcnt lgkmcnt(8)
	v_mfma_f32_32x32x16_bf16 v[112:127], v[230:233], v[238:241], v[112:127]
	v_mfma_f32_32x32x16_bf16 v[96:111], v[230:233], v[242:245], v[96:111]
	ds_read_b64_tr_b16 v[238:239], v249 offset:5120
	ds_read_b64_tr_b16 v[240:241], v249 offset:7168
	ds_read_b64_tr_b16 v[242:243], v249 offset:5632
	ds_read_b64_tr_b16 v[244:245], v249 offset:7680
	s_add_i32 s30, s85, s34
	s_add_i32 m0, s30, 0x8000
	s_nop 0
	global_load_lds_dwordx4 v222, s[2:3] sc1
	s_waitcnt lgkmcnt(8)
	v_mfma_f32_32x32x16_bf16 v[112:127], v[234:237], v[144:147], v[112:127]
	v_mfma_f32_32x32x16_bf16 v[96:111], v[234:237], v[148:151], v[96:111]
	ds_read_b64_tr_b16 v[144:145], v249 offset:16384
	ds_read_b64_tr_b16 v[146:147], v249 offset:18432
	ds_read_b64_tr_b16 v[148:149], v249 offset:16896
	ds_read_b64_tr_b16 v[150:151], v249 offset:18944
	s_add_i32 s30, s85, s34
	s_add_i32 m0, s30, 0xa000
	s_nop 0
	global_load_lds_dwordx4 v221, s[2:3] sc1
	s_waitcnt lgkmcnt(8)
	v_mfma_f32_32x32x16_bf16 v[80:95], v[230:233], v[152:155], v[80:95]
	v_mfma_f32_32x32x16_bf16 v[64:79], v[230:233], v[156:159], v[64:79]
	ds_read_b64_tr_b16 v[152:153], v249 offset:20480
	ds_read_b64_tr_b16 v[154:155], v249 offset:22528
	ds_read_b64_tr_b16 v[156:157], v249 offset:20992
	ds_read_b64_tr_b16 v[158:159], v249 offset:23040
	s_add_i32 s30, s85, s34
	s_add_i32 m0, s30, 0xc000
	s_nop 0
	global_load_lds_dwordx4 v246, s[2:3] sc1
	s_waitcnt lgkmcnt(8)
	v_mfma_f32_32x32x16_bf16 v[80:95], v[234:237], v[238:241], v[80:95]
	v_mfma_f32_32x32x16_bf16 v[64:79], v[234:237], v[242:245], v[64:79]
	ds_read_b64_tr_b16 v[238:239], v249 offset:17408
	ds_read_b64_tr_b16 v[240:241], v249 offset:19456
	ds_read_b64_tr_b16 v[242:243], v249 offset:17920
	ds_read_b64_tr_b16 v[244:245], v249 offset:19968
	s_add_i32 s30, s85, s34
	s_add_i32 m0, s30, 0xe000
	s_nop 0
	global_load_lds_dwordx4 v247, s[2:3] sc1
	s_waitcnt lgkmcnt(8)
	v_mfma_f32_32x32x16_bf16 v[32:47], v[230:233], v[144:147], v[32:47]
	v_mfma_f32_32x32x16_bf16 v[16:31], v[230:233], v[148:151], v[16:31]
	ds_read_b64_tr_b16 v[144:145], v249 offset:21504
	ds_read_b64_tr_b16 v[146:147], v249 offset:23552
	ds_read_b64_tr_b16 v[148:149], v249 offset:22016
	ds_read_b64_tr_b16 v[150:151], v249 offset:24064
	s_add_i32 m0, s34, 0x4000
	s_nop 0
	global_load_lds_dwordx4 v225, s[86:87] sc1
	s_waitcnt lgkmcnt(8)
	v_mfma_f32_32x32x16_bf16 v[32:47], v[234:237], v[152:155], v[32:47]
	v_mfma_f32_32x32x16_bf16 v[16:31], v[234:237], v[156:159], v[16:31]
	s_add_i32 m0, s34, 0x6000
	s_nop 0
	global_load_lds_dwordx4 v223, s[86:87] sc1
	s_waitcnt lgkmcnt(0)
; #define SBAR() __builtin_amdgcn_sched_barrier(0)
; #define PVR(S, DA, DB, vbase) do { S[0] = tr_read<v_rd_off(DA, 0, 0)>(vbase); S[1] = tr_read<v_rd_off(DA, 0, 1)>(vbase); S[2] = tr_read<v_rd_off(DB, 0, 0)>(vbase); S[3] = tr_read<v_rd_off(DB, 0, 1)>(vbase); \
;     S[4] = tr_read<v_rd_off(DA, 1, 0)>(vbase); S[5] = tr_read<v_rd_off(DA, 1, 1)>(vbase); S[6] = tr_read<v_rd_off(DB, 1, 0)>(vbase); S[7] = tr_read<v_rd_off(DB, 1, 1)>(vbase); } while (0)
; #define RAWBAR() do { asm volatile("s_waitcnt lgkmcnt(0)" ::: "memory"); __builtin_amdgcn_s_barrier(); asm volatile("" ::: "memory"); } while (0)
; #define RAWBAR() do { asm volatile("s_waitcnt lgkmcnt(0)" ::: "memory"); __builtin_amdgcn_s_barrier(); asm volatile("" ::: "memory"); } while (0)
; #define RAWBAR() do { asm volatile("s_waitcnt lgkmcnt(0)" ::: "memory"); __builtin_amdgcn_s_barrier(); asm volatile("" ::: "memory"); } while (0)
; #define RAWBAR() do { asm volatile("s_waitcnt lgkmcnt(0)" ::: "memory"); __builtin_amdgcn_s_barrier(); asm volatile("" ::: "memory"); } while (0)
; #define RAWBAR() do { asm volatile("s_waitcnt lgkmcnt(0)" ::: "memory"); __builtin_amdgcn_s_barrier(); asm volatile("" ::: "memory"); } while (0)
; template <int MODE> ...
;     ...
;   for (int j = 0; j < NT; ++j) {
;     const int buf = j & 1;
;     if (j + 1 < NT) { STAGE((j + 1) * KVBLK, buf ^ 1); }
;     const char* Kb = K_lds + buf * 16384;
;     f32x16 pe = {}, po = {};
; #pragma unroll
;     for (int d0 = 0; d0 < 8; d0 += 2) {
;       const bf16x8 k0 = *reinterpret_cast<const bf16x8*>(Kb + KSWZ(krow, (d0 * 16 + hi * 8) * 2));
;       const bf16x8 k1 = *reinterpret_cast<const bf16x8*>(Kb + KSWZ(krow, ((d0 + 1) * 16 + hi * 8) * 2));
;       pe = __builtin_amdgcn_mfma_f32_32x32x16_bf16(k0, qr[d0], pe, 0, 0, 0);
;       po = __builtin_amdgcn_mfma_f32_32x32x16_bf16(k1, qr[d0 + 1], po, 0, 0, 0); }
;     const int vo = vb0 + buf * 32768;
;     s16x4 R0_[8], R1_[8];
;     PVR(R0_, 0, 1, vo);
;     f32x16 p;
; #pragma unroll
;     for (int r = 0; r < 16; ++r) p[r] = __builtin_amdgcn_exp2f(fmaf(pe[r] + po[r], C, negMc));
;     float ps = 0.f;
; #pragma unroll
;     for (int r = 0; r < 16; ++r) ps += p[r];
;     lsum += ps;
;     const bf16x8 own0 = pk8(p, 0), own1 = pk8(p, 8);
;     SBAR();
;     PV_TAIL4(o, vo, vo + 16384, own0, own1);
;     asm volatile("s_waitcnt vmcnt(0)" ::: "memory");
;     RAWBAR();
;   }
	v_mfma_f32_32x32x16_bf16 v[48:63], v[230:233], v[238:241], v[48:63]
	v_mfma_f32_32x32x16_bf16 v[0:15], v[230:233], v[242:245], v[0:15]
	v_mfma_f32_32x32x16_bf16 v[48:63], v[234:237], v[144:147], v[48:63]
	s_add_i32 s84, s84, 0x8000
	s_cmp_eq_u32 s84, 0x18000
	s_cselect_b32 s84, 0, s84
	v_mfma_f32_32x32x16_bf16 v[0:15], v[234:237], v[148:151], v[0:15]
	ds_read_b128 v[230:233], v229 offset:0
	ds_read_b128 v[234:237], v228 offset:0
	ds_read_b128 v[238:241], v227 offset:0
	ds_read_b128 v[242:245], v226 offset:0
	v_exp_f32_e32 v128, v128
	v_exp_f32_e32 v129, v129
	v_exp_f32_e32 v130, v130
	v_exp_f32_e32 v131, v131
	s_waitcnt lgkmcnt(2)
	v_mfma_f32_32x32x16_bf16 v[144:159], v[230:233], v[188:191], 0
	v_mfma_f32_32x32x16_bf16 v[144:159], v[234:237], v[184:187], v[144:159]
	ds_read_b128 v[230:233], v204 offset:0
	ds_read_b128 v[234:237], v205 offset:0
	v_exp_f32_e32 v132, v132
	v_exp_f32_e32 v133, v133
	v_exp_f32_e32 v134, v134
	v_exp_f32_e32 v135, v135
	v_add_f32_e32 v250, v128, v129
	v_add_f32_e32 v250, v130, v250
	v_add_f32_e32 v250, v131, v250
	s_waitcnt lgkmcnt(2)
	v_mfma_f32_32x32x16_bf16 v[144:159], v[238:241], v[180:183], v[144:159]
	v_mfma_f32_32x32x16_bf16 v[144:159], v[242:245], v[176:179], v[144:159]
	ds_read_b128 v[238:241], v206 offset:0
	ds_read_b128 v[242:245], v207 offset:0
	v_exp_f32_e32 v136, v136
	v_exp_f32_e32 v137, v137
	v_exp_f32_e32 v138, v138
	v_exp_f32_e32 v139, v139
	v_add_f32_e32 v250, v132, v250
	v_add_f32_e32 v250, v133, v250
	v_add_f32_e32 v250, v134, v250
	v_add_f32_e32 v250, v135, v250
	s_waitcnt lgkmcnt(2)
	v_mfma_f32_32x32x16_bf16 v[144:159], v[230:233], v[172:175], v[144:159]
	v_mfma_f32_32x32x16_bf16 v[144:159], v[234:237], v[168:171], v[144:159]
	v_exp_f32_e32 v140, v140
	v_exp_f32_e32 v141, v141
	v_exp_f32_e32 v142, v142
	v_exp_f32_e32 v143, v143
	v_add_f32_e32 v250, v136, v250
	v_add_f32_e32 v250, v137, v250
	v_add_f32_e32 v250, v138, v250
	v_add_f32_e32 v250, v139, v250
	v_cvt_pk_bf16_f32 v230, v128, v129
	v_cvt_pk_bf16_f32 v231, v130, v131
	v_cvt_pk_bf16_f32 v232, v132, v133
	v_cvt_pk_bf16_f32 v233, v134, v135
	s_waitcnt lgkmcnt(0)
	v_mfma_f32_32x32x16_bf16 v[144:159], v[238:241], v[164:167], v[144:159]
	v_mfma_f32_32x32x16_bf16 v[144:159], v[242:245], v[160:163], v[144:159]
	s_waitcnt vmcnt(0)
	s_barrier
	s_add_u32 s86, s86, 0x4000
	s_addc_u32 s87, s87, 0
	s_add_u32 s2, s2, 0x8000
	s_addc_u32 s3, s3, 0
	v_add_u32_e32 v249, s84, v218
	s_sub_u32 s85, s84, 0x8000
	s_cmp_eq_u32 s84, 0
	s_cselect_b32 s85, 0x10000, s85
	ds_read_b64_tr_b16 v[238:239], v249 offset:0
	ds_read_b64_tr_b16 v[240:241], v249 offset:2048
	ds_read_b64_tr_b16 v[242:243], v249 offset:512
	ds_read_b64_tr_b16 v[244:245], v249 offset:2560
	ds_read_b64_tr_b16 v[128:129], v249 offset:4096
	ds_read_b64_tr_b16 v[130:131], v249 offset:6144
	ds_read_b64_tr_b16 v[132:133], v249 offset:4608
	ds_read_b64_tr_b16 v[134:135], v249 offset:6656
	v_add_f32_e32 v250, v140, v250
	v_add_f32_e32 v250, v141, v250
	v_add_f32_e32 v250, v142, v250
	v_add_f32_e32 v250, v143, v250
	v_cvt_pk_bf16_f32 v234, v136, v137
	v_cvt_pk_bf16_f32 v235, v138, v139
	v_cvt_pk_bf16_f32 v236, v140, v141
	v_cvt_pk_bf16_f32 v237, v142, v143
	v_add_f32_e32 v219, v219, v250
	ds_read_b64_tr_b16 v[136:137], v249 offset:1024
	ds_read_b64_tr_b16 v[138:139], v249 offset:3072
	ds_read_b64_tr_b16 v[140:141], v249 offset:1536
	ds_read_b64_tr_b16 v[142:143], v249 offset:3584
	s_waitcnt lgkmcnt(8)
	v_mfma_f32_32x32x16_bf16 v[112:127], v[230:233], v[238:241], v[112:127]
	v_mfma_f32_32x32x16_bf16 v[96:111], v[230:233], v[242:245], v[96:111]
	ds_read_b64_tr_b16 v[238:239], v249 offset:5120
	ds_read_b64_tr_b16 v[240:241], v249 offset:7168
	ds_read_b64_tr_b16 v[242:243], v249 offset:5632
	ds_read_b64_tr_b16 v[244:245], v249 offset:7680
	s_add_i32 s30, s85, s34
	s_add_i32 m0, s30, 0x8000
	s_nop 0
	global_load_lds_dwordx4 v222, s[2:3] sc1
	s_waitcnt lgkmcnt(8)
	v_mfma_f32_32x32x16_bf16 v[112:127], v[234:237], v[128:131], v[112:127]
	v_mfma_f32_32x32x16_bf16 v[96:111], v[234:237], v[132:135], v[96:111]
	ds_read_b64_tr_b16 v[128:129], v249 offset:16384
	ds_read_b64_tr_b16 v[130:131], v249 offset:18432
	ds_read_b64_tr_b16 v[132:133], v249 offset:16896
	ds_read_b64_tr_b16 v[134:135], v249 offset:18944
	s_add_i32 s30, s85, s34
	s_add_i32 m0, s30, 0xa000
	s_nop 0
	global_load_lds_dwordx4 v221, s[2:3] sc1
	s_waitcnt lgkmcnt(8)
	v_mfma_f32_32x32x16_bf16 v[80:95], v[230:233], v[136:139], v[80:95]
	v_mfma_f32_32x32x16_bf16 v[64:79], v[230:233], v[140:143], v[64:79]
	ds_read_b64_tr_b16 v[136:137], v249 offset:20480
	ds_read_b64_tr_b16 v[138:139], v249 offset:22528
	ds_read_b64_tr_b16 v[140:141], v249 offset:20992
	ds_read_b64_tr_b16 v[142:143], v249 offset:23040
	s_add_i32 s30, s85, s34
	s_add_i32 m0, s30, 0xc000
	s_nop 0
	global_load_lds_dwordx4 v246, s[2:3] sc1
	s_waitcnt lgkmcnt(8)
	v_mfma_f32_32x32x16_bf16 v[80:95], v[234:237], v[238:241], v[80:95]
	v_mfma_f32_32x32x16_bf16 v[64:79], v[234:237], v[242:245], v[64:79]
	ds_read_b64_tr_b16 v[238:239], v249 offset:17408
	ds_read_b64_tr_b16 v[240:241], v249 offset:19456
	ds_read_b64_tr_b16 v[242:243], v249 offset:17920
	ds_read_b64_tr_b16 v[244:245], v249 offset:19968
	s_add_i32 s30, s85, s34
	s_add_i32 m0, s30, 0xe000
	s_nop 0
	global_load_lds_dwordx4 v247, s[2:3] sc1
	s_waitcnt lgkmcnt(8)
	v_mfma_f32_32x32x16_bf16 v[32:47], v[230:233], v[128:131], v[32:47]
	v_mfma_f32_32x32x16_bf16 v[16:31], v[230:233], v[132:135], v[16:31]
	ds_read_b64_tr_b16 v[128:129], v249 offset:21504
	ds_read_b64_tr_b16 v[130:131], v249 offset:23552
	ds_read_b64_tr_b16 v[132:133], v249 offset:22016
	ds_read_b64_tr_b16 v[134:135], v249 offset:24064
	s_mov_b32 m0, s34
	s_nop 0
	global_load_lds_dwordx4 v225, s[86:87] sc1
	s_waitcnt lgkmcnt(8)
	v_mfma_f32_32x32x16_bf16 v[32:47], v[234:237], v[136:139], v[32:47]
	v_mfma_f32_32x32x16_bf16 v[16:31], v[234:237], v[140:143], v[16:31]
	s_add_i32 m0, s34, 0x2000
	s_nop 0
	global_load_lds_dwordx4 v223, s[86:87] sc1
	s_waitcnt lgkmcnt(0)
	v_mfma_f32_32x32x16_bf16 v[48:63], v[230:233], v[238:241], v[48:63]
	v_mfma_f32_32x32x16_bf16 v[0:15], v[230:233], v[242:245], v[0:15]
	v_mfma_f32_32x32x16_bf16 v[48:63], v[234:237], v[128:131], v[48:63]
	s_add_i32 s84, s84, 0x8000
	s_cmp_eq_u32 s84, 0x18000
	s_cselect_b32 s84, 0, s84
	s_add_i32 s40, s40, 1
	s_cmpk_eq_i32 s40, 0x82
	v_mfma_f32_32x32x16_bf16 v[0:15], v[234:237], v[132:135], v[0:15]
	s_cbranch_scc0 .LattnB_m1
	s_waitcnt vmcnt(0)
	s_barrier
